# v24 + first K iteration peeled with inline-0 C operand (no accumulator clear per unit)
# speedup vs baseline: 1.0052x; 1.0028x over previous
; #define PG8_STAGE(bufoff, gbase, voff) do { _Pragma("unroll") for (int _i = 0; _i < 2; ++_i) \
;         __builtin_amdgcn_global_load_lds((const unsigned*)((const char*)(gbase) + (voff)[_i]), (PG8_LAS unsigned*)(lds + (bufoff) + ldsw + _i * 8192), 16, 0, 0); } while (0)
; #define PG8_LDA(dst, b, h) do { _Pragma("unroll") for (int m = 0; m < 4; ++m) _Pragma("unroll") for (int k = 0; k < 2; ++k) dst[m][k] = *(const PG8_LAS bf16x8*)(lds + PG8_SA(b, h) + aoff + m * 2048 + k * 1024); } while (0)
; #define PG8_WAIT_V(n) asm volatile("s_waitcnt vmcnt(" #n ")" ::: "memory")
; #define PG8_WAIT_L(n) asm volatile("s_waitcnt lgkmcnt(" #n ")" ::: "memory")
; #define PG8_BAR __builtin_amdgcn_s_barrier()
; template <class Epi, class Sched, bool ALIGN_EPI = false, bool SP2 = false, bool F16 = false>
; __device__ __forceinline__ void gemm_phase(PG8_LAS unsigned char* lds, const Gemm g, const Sched& S, const Epi& E) {
;     ...
;         for (int t = 0; t < nt; t += 2) {
;             const bool last = (t == nt - 2);
;             const char* a1 = cA + (size_t)(t + 1) * kstep;
;             const char* a2 = last ? nA : cA + (size_t)(t + 2) * kstep; const char* b2 = last ? nB : cB + (size_t)(t + 2) * kstep;
;             const char* a3 = a2 + kstep; const char* b3 = b2 + kstep;
;             if (last && has_next) S.a_ready(nxt);
;             if constexpr (SP2) {
;             PG8_LDB(B0, 0, 0); PG8_LDB(B1, 0, 1); PG8_SCHED; PG8_LDA(At, 0, 0); PG8_STAGE(PG8_SA(1, 1), a1 + hstepA, voffA);
;             PG8_WAIT_V(8); PG8_WAIT_L(0); PG8_BAR; PG8_MMA(0, 0, At, B0); PG8_MMA(0, 1, At, B1); PG8_BAR; PG8_SCHED;
;             PG8_LDA(At, 0, 1); PG8_STAGE(PG8_SB(0, 0), b2, voffB); PG8_STAGE(PG8_SB(0, 1), b2 + hstepB, voffB); PG8_STAGE(PG8_SA(0, 0), a2, voffA);
;             PG8_WAIT_V(8); PG8_WAIT_L(0); PG8_BAR; PG8_MMA(1, 0, At, B0); PG8_MMA(1, 1, At, B1); PG8_BAR; PG8_SCHED;
;             PG8_LDB(B0, 1, 0); PG8_LDB(B1, 1, 1); PG8_SCHED; PG8_LDA(At, 1, 0); PG8_STAGE(PG8_SA(0, 1), a2 + hstepA, voffA);
;             PG8_WAIT_V(8); PG8_WAIT_L(0); PG8_BAR; PG8_MMA(0, 0, At, B0); PG8_MMA(0, 1, At, B1); PG8_BAR; PG8_SCHED;
;             PG8_LDA(At, 1, 1); PG8_STAGE(PG8_SB(1, 0), b3, voffB); PG8_STAGE(PG8_SB(1, 1), b3 + hstepB, voffB); PG8_STAGE(PG8_SA(1, 0), a3, voffA);
;             PG8_WAIT_V(8); PG8_WAIT_L(0); PG8_BAR; PG8_MMA(1, 0, At, B0); PG8_MMA(1, 1, At, B1); PG8_BAR; PG8_SCHED;
.LBB0_308:
	s_andn2_b64 vcc, exec, s[4:5]
	s_waitcnt vmcnt(0)
	s_cbranch_vccnz .Lzk_gu
	s_add_u32 s52, s52, 0x80
	s_addc_u32 s53, s53, 0
	s_add_u32 s80, s54, 0x100
	s_addc_u32 s81, s55, 0
	s_mov_b32 s54, 0
.Lpk_gu:
	s_add_i32 s82, s54, 2
	s_add_u32 s83, s52, 0x80
	s_addc_u32 s55, s53, 0
	s_add_i32 vcc_lo, 0, 0x10000
	s_cmp_eq_u32 s74, s54
	s_cselect_b32 s55, s39, s55
	s_cselect_b32 s54, s38, s83
	s_cselect_b32 s95, s47, s81
	s_cselect_b32 s94, s46, s80
	s_add_i32 s83, 0, 0x14000
	v_add_u32_e32 v156, vcc_lo, v165
	v_add_u32_e32 v164, s83, v165
	ds_read_b128 v[130:133], v156
	ds_read_b128 v[134:137], v156 offset:1024
	ds_read_b128 v[152:155], v156 offset:2048
	ds_read_b128 v[156:159], v156 offset:3072
	ds_read_b128 v[160:163], v164
	ds_read_b128 v[166:169], v164 offset:1024
	ds_read_b128 v[184:187], v164 offset:2048
	ds_read_b128 v[188:191], v164 offset:3072
	v_lshl_add_u64 v[172:173], s[52:53], 0, v[148:149]
	s_add_i32 m0, s22, 0xc000
	ds_read_b128 v[192:195], v183
	ds_read_b128 v[204:207], v183 offset:1024
	ds_read_b128 v[208:211], v183 offset:2048
	ds_read_b128 v[212:215], v183 offset:3072
	ds_read_b128 v[216:219], v183 offset:4096
	ds_read_b128 v[220:223], v183 offset:5120
	ds_read_b128 v[224:227], v183 offset:6144
	ds_read_b128 v[228:231], v183 offset:7168
	global_load_lds_dwordx4 v[172:173], off
	v_lshl_add_u64 v[172:173], s[52:53], 0, v[150:151]
	s_add_i32 m0, s22, 0xe000
	s_nop 0
	global_load_lds_dwordx4 v[172:173], off
	s_waitcnt vmcnt(8)
	s_waitcnt lgkmcnt(0)
	s_setprio 1
	s_barrier
	v_mfma_f32_16x16x32_f16 v[122:125], v[130:133], v[192:195], 0
	v_mfma_f32_16x16x32_f16 v[114:117], v[152:155], v[192:195], 0
	v_mfma_f32_16x16x32_f16 v[106:109], v[130:133], v[208:211], 0
	v_mfma_f32_16x16x32_f16 v[98:101], v[152:155], v[208:211], 0
	v_mfma_f32_16x16x32_f16 v[90:93], v[130:133], v[216:219], 0
	v_mfma_f32_16x16x32_f16 v[82:85], v[152:155], v[216:219], 0
	v_mfma_f32_16x16x32_f16 v[74:77], v[130:133], v[224:227], 0
	v_mfma_f32_16x16x32_f16 v[66:69], v[152:155], v[224:227], 0
	v_mfma_f32_16x16x32_f16 v[122:125], v[134:137], v[204:207], v[122:125]
	v_mfma_f32_16x16x32_f16 v[114:117], v[156:159], v[204:207], v[114:117]
	v_mfma_f32_16x16x32_f16 v[106:109], v[134:137], v[212:215], v[106:109]
	v_mfma_f32_16x16x32_f16 v[98:101], v[156:159], v[212:215], v[98:101]
	v_mfma_f32_16x16x32_f16 v[90:93], v[134:137], v[220:223], v[90:93]
	v_mfma_f32_16x16x32_f16 v[82:85], v[156:159], v[220:223], v[82:85]
	v_mfma_f32_16x16x32_f16 v[74:77], v[134:137], v[228:231], v[74:77]
	v_mfma_f32_16x16x32_f16 v[66:69], v[156:159], v[228:231], v[66:69]
	v_mfma_f32_16x16x32_f16 v[126:129], v[160:163], v[192:195], 0
	v_mfma_f32_16x16x32_f16 v[118:121], v[184:187], v[192:195], 0
	v_mfma_f32_16x16x32_f16 v[110:113], v[160:163], v[208:211], 0
	v_mfma_f32_16x16x32_f16 v[102:105], v[184:187], v[208:211], 0
	v_mfma_f32_16x16x32_f16 v[94:97], v[160:163], v[216:219], 0
	v_mfma_f32_16x16x32_f16 v[86:89], v[184:187], v[216:219], 0
	v_mfma_f32_16x16x32_f16 v[78:81], v[160:163], v[224:227], 0
	v_mfma_f32_16x16x32_f16 v[70:73], v[184:187], v[224:227], 0
	v_mfma_f32_16x16x32_f16 v[126:129], v[166:169], v[204:207], v[126:129]
	v_mfma_f32_16x16x32_f16 v[118:121], v[188:191], v[204:207], v[118:121]
	v_mfma_f32_16x16x32_f16 v[110:113], v[166:169], v[212:215], v[110:113]
	v_mfma_f32_16x16x32_f16 v[102:105], v[188:191], v[212:215], v[102:105]
	v_mfma_f32_16x16x32_f16 v[94:97], v[166:169], v[220:223], v[94:97]
	v_mfma_f32_16x16x32_f16 v[86:89], v[188:191], v[220:223], v[86:89]
	v_mfma_f32_16x16x32_f16 v[78:81], v[166:169], v[228:231], v[78:81]
	v_mfma_f32_16x16x32_f16 v[70:73], v[188:191], v[228:231], v[70:73]
	s_barrier
	s_setprio 0
	s_add_i32 vcc_lo, vcc_lo, s2
	v_lshl_add_u64 v[172:173], s[94:95], 0, v[142:143]
	s_mov_b32 m0, vcc_lo
	ds_read_b128 v[192:195], v183 offset:16384
	ds_read_b128 v[204:207], v183 offset:17408
	ds_read_b128 v[208:211], v183 offset:18432
	ds_read_b128 v[212:215], v183 offset:19456
	ds_read_b128 v[216:219], v183 offset:20480
	ds_read_b128 v[220:223], v183 offset:21504
	ds_read_b128 v[224:227], v183 offset:22528
	ds_read_b128 v[228:231], v183 offset:23552
	global_load_lds_dwordx4 v[172:173], off
	s_add_i32 m0, vcc_lo, 0x2000
	v_lshl_add_u64 v[176:177], s[94:95], 0, v[138:139]
	s_add_u32 s94, s94, s48
	s_addc_u32 s95, s95, 0
	s_add_i32 s83, s83, s2
	global_load_lds_dwordx4 v[176:177], off
	v_lshl_add_u64 v[196:197], s[94:95], 0, v[142:143]
	s_mov_b32 m0, s83
	v_lshl_add_u64 v[232:233], s[94:95], 0, v[138:139]
	global_load_lds_dwordx4 v[196:197], off
	s_add_i32 m0, s83, 0x2000
	v_lshl_add_u64 v[234:235], s[54:55], 0, v[144:145]
	global_load_lds_dwordx4 v[232:233], off
	s_mov_b32 m0, s22
	v_lshl_add_u64 v[236:237], s[54:55], 0, v[140:141]
	global_load_lds_dwordx4 v[234:235], off
	s_mov_b32 m0, s33
	s_nop 0
	global_load_lds_dwordx4 v[236:237], off
	s_waitcnt vmcnt(8)
	s_waitcnt lgkmcnt(0)
	s_setprio 1
	s_barrier
; #define PG8_STAGE(bufoff, gbase, voff) do { _Pragma("unroll") for (int _i = 0; _i < 2; ++_i) \
;         __builtin_amdgcn_global_load_lds((const unsigned*)((const char*)(gbase) + (voff)[_i]), (PG8_LAS unsigned*)(lds + (bufoff) + ldsw + _i * 8192), 16, 0, 0); } while (0)
; #define PG8_LDA(dst, b, h) do { _Pragma("unroll") for (int m = 0; m < 4; ++m) _Pragma("unroll") for (int k = 0; k < 2; ++k) dst[m][k] = *(const PG8_LAS bf16x8*)(lds + PG8_SA(b, h) + aoff + m * 2048 + k * 1024); } while (0)
; #define PG8_WAIT_V(n) asm volatile("s_waitcnt vmcnt(" #n ")" ::: "memory")
; #define PG8_WAIT_L(n) asm volatile("s_waitcnt lgkmcnt(" #n ")" ::: "memory")
; #define PG8_BAR __builtin_amdgcn_s_barrier()
; template <class Epi, class Sched, bool ALIGN_EPI = false, bool SP2 = false, bool F16 = false>
; __device__ __forceinline__ void gemm_phase(PG8_LAS unsigned char* lds, const Gemm g, const Sched& S, const Epi& E) {
;     ...
;         for (int t = 0; t < nt; t += 2) {
;             const bool last = (t == nt - 2);
;             const char* a1 = cA + (size_t)(t + 1) * kstep;
;             const char* a2 = last ? nA : cA + (size_t)(t + 2) * kstep; const char* b2 = last ? nB : cB + (size_t)(t + 2) * kstep;
;             const char* a3 = a2 + kstep; const char* b3 = b2 + kstep;
;             if (last && has_next) S.a_ready(nxt);
;             if constexpr (SP2) {
;             PG8_LDB(B0, 0, 0); PG8_LDB(B1, 0, 1); PG8_SCHED; PG8_LDA(At, 0, 0); PG8_STAGE(PG8_SA(1, 1), a1 + hstepA, voffA);
;             PG8_WAIT_V(8); PG8_WAIT_L(0); PG8_BAR; PG8_MMA(0, 0, At, B0); PG8_MMA(0, 1, At, B1); PG8_BAR; PG8_SCHED;
;             PG8_LDA(At, 0, 1); PG8_STAGE(PG8_SB(0, 0), b2, voffB); PG8_STAGE(PG8_SB(0, 1), b2 + hstepB, voffB); PG8_STAGE(PG8_SA(0, 0), a2, voffA);
;             PG8_WAIT_V(8); PG8_WAIT_L(0); PG8_BAR; PG8_MMA(1, 0, At, B0); PG8_MMA(1, 1, At, B1); PG8_BAR; PG8_SCHED;
;             PG8_LDB(B0, 1, 0); PG8_LDB(B1, 1, 1); PG8_SCHED; PG8_LDA(At, 1, 0); PG8_STAGE(PG8_SA(0, 1), a2 + hstepA, voffA);
;             PG8_WAIT_V(8); PG8_WAIT_L(0); PG8_BAR; PG8_MMA(0, 0, At, B0); PG8_MMA(0, 1, At, B1); PG8_BAR; PG8_SCHED;
;             PG8_LDA(At, 1, 1); PG8_STAGE(PG8_SB(1, 0), b3, voffB); PG8_STAGE(PG8_SB(1, 1), b3 + hstepB, voffB); PG8_STAGE(PG8_SA(1, 0), a3, voffA);
;             PG8_WAIT_V(8); PG8_WAIT_L(0); PG8_BAR; PG8_MMA(1, 0, At, B0); PG8_MMA(1, 1, At, B1); PG8_BAR; PG8_SCHED;
	v_mfma_f32_16x16x32_f16 v[58:61], v[130:133], v[192:195], 0
	v_mfma_f32_16x16x32_f16 v[50:53], v[152:155], v[192:195], 0
	v_mfma_f32_16x16x32_f16 v[42:45], v[130:133], v[208:211], 0
	v_mfma_f32_16x16x32_f16 v[34:37], v[152:155], v[208:211], 0
	v_mfma_f32_16x16x32_f16 v[26:29], v[130:133], v[216:219], 0
	v_mfma_f32_16x16x32_f16 v[18:21], v[152:155], v[216:219], 0
	v_mfma_f32_16x16x32_f16 v[10:13], v[130:133], v[224:227], 0
	v_mfma_f32_16x16x32_f16 v[6:9], v[152:155], v[224:227], 0
	v_mfma_f32_16x16x32_f16 v[58:61], v[134:137], v[204:207], v[58:61]
	v_mfma_f32_16x16x32_f16 v[50:53], v[156:159], v[204:207], v[50:53]
	v_mfma_f32_16x16x32_f16 v[42:45], v[134:137], v[212:215], v[42:45]
	v_mfma_f32_16x16x32_f16 v[34:37], v[156:159], v[212:215], v[34:37]
	v_mfma_f32_16x16x32_f16 v[26:29], v[134:137], v[220:223], v[26:29]
	v_mfma_f32_16x16x32_f16 v[18:21], v[156:159], v[220:223], v[18:21]
	v_mfma_f32_16x16x32_f16 v[10:13], v[134:137], v[228:231], v[10:13]
	v_mfma_f32_16x16x32_f16 v[6:9], v[156:159], v[228:231], v[6:9]
	v_mfma_f32_16x16x32_f16 v[62:65], v[160:163], v[192:195], 0
	v_mfma_f32_16x16x32_f16 v[54:57], v[184:187], v[192:195], 0
	v_mfma_f32_16x16x32_f16 v[46:49], v[160:163], v[208:211], 0
	v_mfma_f32_16x16x32_f16 v[38:41], v[184:187], v[208:211], 0
	v_mfma_f32_16x16x32_f16 v[30:33], v[160:163], v[216:219], 0
	v_mfma_f32_16x16x32_f16 v[22:25], v[184:187], v[216:219], 0
	v_mfma_f32_16x16x32_f16 v[14:17], v[160:163], v[224:227], 0
	v_mfma_f32_16x16x32_f16 v[2:5], v[184:187], v[224:227], 0
	v_mfma_f32_16x16x32_f16 v[62:65], v[166:169], v[204:207], v[62:65]
	v_mfma_f32_16x16x32_f16 v[54:57], v[188:191], v[204:207], v[54:57]
	v_mfma_f32_16x16x32_f16 v[46:49], v[166:169], v[212:215], v[46:49]
	v_mfma_f32_16x16x32_f16 v[38:41], v[188:191], v[212:215], v[38:41]
	v_mfma_f32_16x16x32_f16 v[30:33], v[166:169], v[220:223], v[30:33]
	v_mfma_f32_16x16x32_f16 v[22:25], v[188:191], v[220:223], v[22:25]
	v_mfma_f32_16x16x32_f16 v[14:17], v[166:169], v[228:231], v[14:17]
	v_mfma_f32_16x16x32_f16 v[2:5], v[188:191], v[228:231], v[2:5]
	s_barrier
	s_setprio 0
	s_add_i32 s83, 0, 0x18000
	s_add_i32 s94, 0, 0x1c000
	v_add_u32_e32 v156, s83, v165
	v_add_u32_e32 v164, s94, v165
	ds_read_b128 v[130:133], v156
	ds_read_b128 v[134:137], v156 offset:1024
	ds_read_b128 v[152:155], v156 offset:2048
	ds_read_b128 v[156:159], v156 offset:3072
	ds_read_b128 v[160:163], v164
	ds_read_b128 v[166:169], v164 offset:1024
	ds_read_b128 v[184:187], v164 offset:2048
	ds_read_b128 v[188:191], v164 offset:3072
	s_add_u32 s54, s54, s8
	s_addc_u32 s55, s55, 0
	s_mov_b32 m0, s12
	v_lshl_add_u64 v[238:239], s[54:55], 0, v[144:145]
	ds_read_b128 v[192:195], v183 offset:32768
	ds_read_b128 v[204:207], v183 offset:33792
	ds_read_b128 v[208:211], v183 offset:34816
	ds_read_b128 v[212:215], v183 offset:35840
	ds_read_b128 v[216:219], v183 offset:36864
	ds_read_b128 v[220:223], v183 offset:37888
	ds_read_b128 v[224:227], v183 offset:38912
	ds_read_b128 v[228:231], v183 offset:39936
	global_load_lds_dwordx4 v[238:239], off
	v_lshl_add_u64 v[238:239], s[54:55], 0, v[140:141]
	s_mov_b32 m0, s13
	s_nop 0
	global_load_lds_dwordx4 v[238:239], off
	s_waitcnt vmcnt(8)
	s_waitcnt lgkmcnt(0)
	s_setprio 1
	s_barrier
	v_mfma_f32_16x16x32_f16 v[122:125], v[130:133], v[192:195], v[122:125]
	v_mfma_f32_16x16x32_f16 v[114:117], v[152:155], v[192:195], v[114:117]
	v_mfma_f32_16x16x32_f16 v[106:109], v[130:133], v[208:211], v[106:109]
	v_mfma_f32_16x16x32_f16 v[98:101], v[152:155], v[208:211], v[98:101]
	v_mfma_f32_16x16x32_f16 v[90:93], v[130:133], v[216:219], v[90:93]
	v_mfma_f32_16x16x32_f16 v[82:85], v[152:155], v[216:219], v[82:85]
	v_mfma_f32_16x16x32_f16 v[74:77], v[130:133], v[224:227], v[74:77]
	v_mfma_f32_16x16x32_f16 v[66:69], v[152:155], v[224:227], v[66:69]
	v_mfma_f32_16x16x32_f16 v[122:125], v[134:137], v[204:207], v[122:125]
	v_mfma_f32_16x16x32_f16 v[114:117], v[156:159], v[204:207], v[114:117]
	v_mfma_f32_16x16x32_f16 v[106:109], v[134:137], v[212:215], v[106:109]
	v_mfma_f32_16x16x32_f16 v[98:101], v[156:159], v[212:215], v[98:101]
	v_mfma_f32_16x16x32_f16 v[90:93], v[134:137], v[220:223], v[90:93]
	v_mfma_f32_16x16x32_f16 v[82:85], v[156:159], v[220:223], v[82:85]
	v_mfma_f32_16x16x32_f16 v[74:77], v[134:137], v[228:231], v[74:77]
	v_mfma_f32_16x16x32_f16 v[66:69], v[156:159], v[228:231], v[66:69]
	v_mfma_f32_16x16x32_f16 v[126:129], v[160:163], v[192:195], v[126:129]
	v_mfma_f32_16x16x32_f16 v[118:121], v[184:187], v[192:195], v[118:121]
	v_mfma_f32_16x16x32_f16 v[110:113], v[160:163], v[208:211], v[110:113]
	v_mfma_f32_16x16x32_f16 v[102:105], v[184:187], v[208:211], v[102:105]
	v_mfma_f32_16x16x32_f16 v[94:97], v[160:163], v[216:219], v[94:97]
	v_mfma_f32_16x16x32_f16 v[86:89], v[184:187], v[216:219], v[86:89]
	v_mfma_f32_16x16x32_f16 v[78:81], v[160:163], v[224:227], v[78:81]
	v_mfma_f32_16x16x32_f16 v[70:73], v[184:187], v[224:227], v[70:73]
	v_mfma_f32_16x16x32_f16 v[126:129], v[166:169], v[204:207], v[126:129]
	v_mfma_f32_16x16x32_f16 v[118:121], v[188:191], v[204:207], v[118:121]
	v_mfma_f32_16x16x32_f16 v[110:113], v[166:169], v[212:215], v[110:113]
	v_mfma_f32_16x16x32_f16 v[102:105], v[188:191], v[212:215], v[102:105]
	v_mfma_f32_16x16x32_f16 v[94:97], v[166:169], v[220:223], v[94:97]
	v_mfma_f32_16x16x32_f16 v[86:89], v[188:191], v[220:223], v[86:89]
	v_mfma_f32_16x16x32_f16 v[78:81], v[166:169], v[228:231], v[78:81]
	v_mfma_f32_16x16x32_f16 v[70:73], v[188:191], v[228:231], v[70:73]
	s_barrier
; #define PG8_STAGE(bufoff, gbase, voff) do { _Pragma("unroll") for (int _i = 0; _i < 2; ++_i) \
;         __builtin_amdgcn_global_load_lds((const unsigned*)((const char*)(gbase) + (voff)[_i]), (PG8_LAS unsigned*)(lds + (bufoff) + ldsw + _i * 8192), 16, 0, 0); } while (0)
; #define PG8_LDA(dst, b, h) do { _Pragma("unroll") for (int m = 0; m < 4; ++m) _Pragma("unroll") for (int k = 0; k < 2; ++k) dst[m][k] = *(const PG8_LAS bf16x8*)(lds + PG8_SA(b, h) + aoff + m * 2048 + k * 1024); } while (0)
; #define PG8_WAIT_V(n) asm volatile("s_waitcnt vmcnt(" #n ")" ::: "memory")
; #define PG8_WAIT_L(n) asm volatile("s_waitcnt lgkmcnt(" #n ")" ::: "memory")
; #define PG8_BAR __builtin_amdgcn_s_barrier()
; template <class Epi, class Sched, bool ALIGN_EPI = false, bool SP2 = false, bool F16 = false>
; __device__ __forceinline__ void gemm_phase(PG8_LAS unsigned char* lds, const Gemm g, const Sched& S, const Epi& E) {
;     ...
;         for (int t = 0; t < nt; t += 2) {
;             const bool last = (t == nt - 2);
;             const char* a1 = cA + (size_t)(t + 1) * kstep;
;             const char* a2 = last ? nA : cA + (size_t)(t + 2) * kstep; const char* b2 = last ? nB : cB + (size_t)(t + 2) * kstep;
;             const char* a3 = a2 + kstep; const char* b3 = b2 + kstep;
;             if (last && has_next) S.a_ready(nxt);
;             if constexpr (SP2) {
;             PG8_LDB(B0, 0, 0); PG8_LDB(B1, 0, 1); PG8_SCHED; PG8_LDA(At, 0, 0); PG8_STAGE(PG8_SA(1, 1), a1 + hstepA, voffA);
;             PG8_WAIT_V(8); PG8_WAIT_L(0); PG8_BAR; PG8_MMA(0, 0, At, B0); PG8_MMA(0, 1, At, B1); PG8_BAR; PG8_SCHED;
;             PG8_LDA(At, 0, 1); PG8_STAGE(PG8_SB(0, 0), b2, voffB); PG8_STAGE(PG8_SB(0, 1), b2 + hstepB, voffB); PG8_STAGE(PG8_SA(0, 0), a2, voffA);
;             PG8_WAIT_V(8); PG8_WAIT_L(0); PG8_BAR; PG8_MMA(1, 0, At, B0); PG8_MMA(1, 1, At, B1); PG8_BAR; PG8_SCHED;
;             PG8_LDB(B0, 1, 0); PG8_LDB(B1, 1, 1); PG8_SCHED; PG8_LDA(At, 1, 0); PG8_STAGE(PG8_SA(0, 1), a2 + hstepA, voffA);
;             PG8_WAIT_V(8); PG8_WAIT_L(0); PG8_BAR; PG8_MMA(0, 0, At, B0); PG8_MMA(0, 1, At, B1); PG8_BAR; PG8_SCHED;
;             PG8_LDA(At, 1, 1); PG8_STAGE(PG8_SB(1, 0), b3, voffB); PG8_STAGE(PG8_SB(1, 1), b3 + hstepB, voffB); PG8_STAGE(PG8_SA(1, 0), a3, voffA);
;             PG8_WAIT_V(8); PG8_WAIT_L(0); PG8_BAR; PG8_MMA(1, 0, At, B0); PG8_MMA(1, 1, At, B1); PG8_BAR; PG8_SCHED;
	s_setprio 0
	s_add_i32 s54, s83, s2
	v_lshl_add_u64 v[172:173], v[172:173], 0, s[92:93]
	s_mov_b32 m0, s54
	ds_read_b128 v[192:195], v183 offset:49152
	ds_read_b128 v[204:207], v183 offset:50176
	ds_read_b128 v[208:211], v183 offset:51200
	ds_read_b128 v[212:215], v183 offset:52224
	ds_read_b128 v[216:219], v183 offset:53248
	ds_read_b128 v[220:223], v183 offset:54272
	ds_read_b128 v[224:227], v183 offset:55296
	ds_read_b128 v[228:231], v183 offset:56320
	global_load_lds_dwordx4 v[172:173], off
	v_lshl_add_u64 v[172:173], v[176:177], 0, s[92:93]
	s_add_i32 m0, s54, 0x2000
	s_add_i32 s54, s94, s2
	global_load_lds_dwordx4 v[172:173], off
	v_lshl_add_u64 v[172:173], v[196:197], 0, s[92:93]
	s_mov_b32 m0, s54
	s_nop 0
	global_load_lds_dwordx4 v[172:173], off
	v_lshl_add_u64 v[172:173], v[232:233], 0, s[92:93]
	s_add_i32 m0, s54, 0x2000
	s_nop 0
	global_load_lds_dwordx4 v[172:173], off
	v_lshl_add_u64 v[172:173], v[234:235], 0, s[92:93]
	s_mov_b32 m0, s35
	s_nop 0
	global_load_lds_dwordx4 v[172:173], off
	v_lshl_add_u64 v[172:173], v[236:237], 0, s[92:93]
	s_mov_b32 m0, s59
	s_nop 0
	global_load_lds_dwordx4 v[172:173], off
	s_waitcnt vmcnt(8)
	s_waitcnt lgkmcnt(0)
	s_setprio 1
	s_barrier
	v_mfma_f32_16x16x32_f16 v[58:61], v[130:133], v[192:195], v[58:61]
	v_mfma_f32_16x16x32_f16 v[50:53], v[152:155], v[192:195], v[50:53]
	v_mfma_f32_16x16x32_f16 v[42:45], v[130:133], v[208:211], v[42:45]
	v_mfma_f32_16x16x32_f16 v[34:37], v[152:155], v[208:211], v[34:37]
	v_mfma_f32_16x16x32_f16 v[26:29], v[130:133], v[216:219], v[26:29]
	v_mfma_f32_16x16x32_f16 v[18:21], v[152:155], v[216:219], v[18:21]
	v_mfma_f32_16x16x32_f16 v[10:13], v[130:133], v[224:227], v[10:13]
	v_mfma_f32_16x16x32_f16 v[6:9], v[152:155], v[224:227], v[6:9]
	v_mfma_f32_16x16x32_f16 v[58:61], v[134:137], v[204:207], v[58:61]
	v_mfma_f32_16x16x32_f16 v[50:53], v[156:159], v[204:207], v[50:53]
	v_mfma_f32_16x16x32_f16 v[42:45], v[134:137], v[212:215], v[42:45]
	v_mfma_f32_16x16x32_f16 v[34:37], v[156:159], v[212:215], v[34:37]
	v_mfma_f32_16x16x32_f16 v[26:29], v[134:137], v[220:223], v[26:29]
	v_mfma_f32_16x16x32_f16 v[18:21], v[156:159], v[220:223], v[18:21]
	v_mfma_f32_16x16x32_f16 v[10:13], v[134:137], v[228:231], v[10:13]
	v_mfma_f32_16x16x32_f16 v[6:9], v[156:159], v[228:231], v[6:9]
	v_mfma_f32_16x16x32_f16 v[62:65], v[160:163], v[192:195], v[62:65]
	v_mfma_f32_16x16x32_f16 v[54:57], v[184:187], v[192:195], v[54:57]
	v_mfma_f32_16x16x32_f16 v[46:49], v[160:163], v[208:211], v[46:49]
	v_mfma_f32_16x16x32_f16 v[38:41], v[184:187], v[208:211], v[38:41]
	v_mfma_f32_16x16x32_f16 v[30:33], v[160:163], v[216:219], v[30:33]
	v_mfma_f32_16x16x32_f16 v[22:25], v[184:187], v[216:219], v[22:25]
	v_mfma_f32_16x16x32_f16 v[14:17], v[160:163], v[224:227], v[14:17]
	v_mfma_f32_16x16x32_f16 v[2:5], v[184:187], v[224:227], v[2:5]
	v_mfma_f32_16x16x32_f16 v[62:65], v[166:169], v[204:207], v[62:65]
	v_mfma_f32_16x16x32_f16 v[54:57], v[188:191], v[204:207], v[54:57]
	v_mfma_f32_16x16x32_f16 v[46:49], v[166:169], v[212:215], v[46:49]
	v_mfma_f32_16x16x32_f16 v[38:41], v[188:191], v[212:215], v[38:41]
	v_mfma_f32_16x16x32_f16 v[30:33], v[166:169], v[220:223], v[30:33]
	v_mfma_f32_16x16x32_f16 v[22:25], v[188:191], v[220:223], v[22:25]
	v_mfma_f32_16x16x32_f16 v[14:17], v[166:169], v[228:231], v[14:17]
	v_mfma_f32_16x16x32_f16 v[2:5], v[188:191], v[228:231], v[2:5]
	s_barrier
	s_setprio 0
	s_add_u32 s52, s52, 0x100
	s_addc_u32 s53, s53, 0
	s_add_u32 s80, s80, 0x100
	s_addc_u32 s81, s81, 0
	s_cmp_ge_u32 s82, s65
	s_mov_b32 s54, s82
	s_cbranch_scc1 .LBB0_311

; #define PG8_STAGE(bufoff, gbase, voff) do { _Pragma("unroll") for (int _i = 0; _i < 2; ++_i) \
;         __builtin_amdgcn_global_load_lds((const unsigned*)((const char*)(gbase) + (voff)[_i]), (PG8_LAS unsigned*)(lds + (bufoff) + ldsw + _i * 8192), 16, 0, 0); } while (0)
; #define PG8_LDA(dst, b, h) do { _Pragma("unroll") for (int m = 0; m < 4; ++m) _Pragma("unroll") for (int k = 0; k < 2; ++k) dst[m][k] = *(const PG8_LAS bf16x8*)(lds + PG8_SA(b, h) + aoff + m * 2048 + k * 1024); } while (0)
; #define PG8_WAIT_V(n) asm volatile("s_waitcnt vmcnt(" #n ")" ::: "memory")
; #define PG8_WAIT_L(n) asm volatile("s_waitcnt lgkmcnt(" #n ")" ::: "memory")
; #define PG8_BAR __builtin_amdgcn_s_barrier()
; template <class Epi, class Sched, bool ALIGN_EPI = false, bool SP2 = false, bool F16 = false>
; __device__ __forceinline__ void gemm_phase(PG8_LAS unsigned char* lds, const Gemm g, const Sched& S, const Epi& E) {
;     ...
;         for (int t = 0; t < nt; t += 2) {
;             const bool last = (t == nt - 2);
;             const char* a1 = cA + (size_t)(t + 1) * kstep;
;             const char* a2 = last ? nA : cA + (size_t)(t + 2) * kstep; const char* b2 = last ? nB : cB + (size_t)(t + 2) * kstep;
;             const char* a3 = a2 + kstep; const char* b3 = b2 + kstep;
;             if (last && has_next) S.a_ready(nxt);
;             if constexpr (SP2) {
;             PG8_LDB(B0, 0, 0); PG8_LDB(B1, 0, 1); PG8_SCHED; PG8_LDA(At, 0, 0); PG8_STAGE(PG8_SA(1, 1), a1 + hstepA, voffA);
;             PG8_WAIT_V(8); PG8_WAIT_L(0); PG8_BAR; PG8_MMA(0, 0, At, B0); PG8_MMA(0, 1, At, B1); PG8_BAR; PG8_SCHED;
;             PG8_LDA(At, 0, 1); PG8_STAGE(PG8_SB(0, 0), b2, voffB); PG8_STAGE(PG8_SB(0, 1), b2 + hstepB, voffB); PG8_STAGE(PG8_SA(0, 0), a2, voffA);
;             PG8_WAIT_V(8); PG8_WAIT_L(0); PG8_BAR; PG8_MMA(1, 0, At, B0); PG8_MMA(1, 1, At, B1); PG8_BAR; PG8_SCHED;
;             PG8_LDB(B0, 1, 0); PG8_LDB(B1, 1, 1); PG8_SCHED; PG8_LDA(At, 1, 0); PG8_STAGE(PG8_SA(0, 1), a2 + hstepA, voffA);
;             PG8_WAIT_V(8); PG8_WAIT_L(0); PG8_BAR; PG8_MMA(0, 0, At, B0); PG8_MMA(0, 1, At, B1); PG8_BAR; PG8_SCHED;
;             PG8_LDA(At, 1, 1); PG8_STAGE(PG8_SB(1, 0), b3, voffB); PG8_STAGE(PG8_SB(1, 1), b3 + hstepB, voffB); PG8_STAGE(PG8_SA(1, 0), a3, voffA);
;             PG8_WAIT_V(8); PG8_WAIT_L(0); PG8_BAR; PG8_MMA(1, 0, At, B0); PG8_MMA(1, 1, At, B1); PG8_BAR; PG8_SCHED;
.LBB0_343:
	s_andn2_b64 vcc, exec, s[4:5]
	s_waitcnt vmcnt(0)
	s_cbranch_vccnz .Lzk_rs
	s_add_u32 s52, s52, 0x80
	s_addc_u32 s53, s53, 0
	s_add_u32 s79, s54, 0x100
	s_addc_u32 s80, s55, 0
	s_mov_b32 s54, 0
.Lpk_rs:
	s_add_i32 s81, s54, 2
	s_add_u32 s82, s52, 0x80
	s_addc_u32 s55, s53, 0
	s_add_i32 s94, 0, 0x10000
	s_cmp_eq_u32 s74, s54
	s_cselect_b32 s55, s41, s55
	s_cselect_b32 s54, s40, s82
	s_cselect_b32 s83, s47, s80
	s_cselect_b32 s82, s46, s79
	s_add_i32 s95, 0, 0x14000
	v_add_u32_e32 v152, s94, v158
	v_add_u32_e32 v156, s95, v158
	ds_read_b128 v[130:133], v152
	ds_read_b128 v[134:137], v152 offset:1024
	ds_read_b128 v[148:151], v152 offset:2048
	ds_read_b128 v[152:155], v152 offset:3072
	ds_read_b128 v[162:165], v156
	ds_read_b128 v[166:169], v156 offset:1024
	ds_read_b128 v[170:173], v156 offset:2048
	ds_read_b128 v[182:185], v156 offset:3072
	v_lshl_add_u64 v[156:157], s[52:53], 0, v[144:145]
	s_add_i32 m0, s3, 0xc000
	ds_read_b128 v[186:189], v160
	ds_read_b128 v[190:193], v160 offset:1024
	ds_read_b128 v[194:197], v160 offset:2048
	ds_read_b128 v[204:207], v160 offset:3072
	ds_read_b128 v[208:211], v160 offset:4096
	ds_read_b128 v[212:215], v160 offset:5120
	ds_read_b128 v[216:219], v160 offset:6144
	ds_read_b128 v[220:223], v160 offset:7168
	global_load_lds_dwordx4 v[156:157], off
	v_lshl_add_u64 v[156:157], s[52:53], 0, v[146:147]
	s_add_i32 m0, s3, 0xe000
	s_nop 0
	global_load_lds_dwordx4 v[156:157], off
	s_waitcnt vmcnt(8)
	s_waitcnt lgkmcnt(0)
	s_setprio 1
	s_barrier
	v_mfma_f32_16x16x32_bf16 v[122:125], v[130:133], v[186:189], 0
	v_mfma_f32_16x16x32_bf16 v[126:129], v[148:151], v[186:189], 0
	v_mfma_f32_16x16x32_bf16 v[110:113], v[130:133], v[194:197], 0
	v_mfma_f32_16x16x32_bf16 v[106:109], v[148:151], v[194:197], 0
	v_mfma_f32_16x16x32_bf16 v[94:97], v[130:133], v[208:211], 0
	v_mfma_f32_16x16x32_bf16 v[90:93], v[148:151], v[208:211], 0
	v_mfma_f32_16x16x32_bf16 v[78:81], v[130:133], v[216:219], 0
	v_mfma_f32_16x16x32_bf16 v[74:77], v[148:151], v[216:219], 0
	v_mfma_f32_16x16x32_bf16 v[122:125], v[134:137], v[190:193], v[122:125]
	v_mfma_f32_16x16x32_bf16 v[126:129], v[152:155], v[190:193], v[126:129]
	v_mfma_f32_16x16x32_bf16 v[110:113], v[134:137], v[204:207], v[110:113]
	v_mfma_f32_16x16x32_bf16 v[106:109], v[152:155], v[204:207], v[106:109]
	v_mfma_f32_16x16x32_bf16 v[94:97], v[134:137], v[212:215], v[94:97]
	v_mfma_f32_16x16x32_bf16 v[90:93], v[152:155], v[212:215], v[90:93]
	v_mfma_f32_16x16x32_bf16 v[78:81], v[134:137], v[220:223], v[78:81]
	v_mfma_f32_16x16x32_bf16 v[74:77], v[152:155], v[220:223], v[74:77]
	v_mfma_f32_16x16x32_bf16 v[118:121], v[162:165], v[186:189], 0
	v_mfma_f32_16x16x32_bf16 v[114:117], v[170:173], v[186:189], 0
	v_mfma_f32_16x16x32_bf16 v[102:105], v[162:165], v[194:197], 0
	v_mfma_f32_16x16x32_bf16 v[98:101], v[170:173], v[194:197], 0
	v_mfma_f32_16x16x32_bf16 v[86:89], v[162:165], v[208:211], 0
	v_mfma_f32_16x16x32_bf16 v[82:85], v[170:173], v[208:211], 0
	v_mfma_f32_16x16x32_bf16 v[70:73], v[162:165], v[216:219], 0
	v_mfma_f32_16x16x32_bf16 v[66:69], v[170:173], v[216:219], 0
	v_mfma_f32_16x16x32_bf16 v[118:121], v[166:169], v[190:193], v[118:121]
	v_mfma_f32_16x16x32_bf16 v[114:117], v[182:185], v[190:193], v[114:117]
	v_mfma_f32_16x16x32_bf16 v[102:105], v[166:169], v[204:207], v[102:105]
	v_mfma_f32_16x16x32_bf16 v[98:101], v[182:185], v[204:207], v[98:101]
	v_mfma_f32_16x16x32_bf16 v[86:89], v[166:169], v[212:215], v[86:89]
	v_mfma_f32_16x16x32_bf16 v[82:85], v[182:185], v[212:215], v[82:85]
	v_mfma_f32_16x16x32_bf16 v[70:73], v[166:169], v[220:223], v[70:73]
	v_mfma_f32_16x16x32_bf16 v[66:69], v[182:185], v[220:223], v[66:69]
	s_barrier
	s_setprio 0
	s_add_i32 s94, s94, s2
	v_lshl_add_u64 v[156:157], s[82:83], 0, v[174:175]
	s_mov_b32 m0, s94
	ds_read_b128 v[186:189], v160 offset:16384
	ds_read_b128 v[190:193], v160 offset:17408
	ds_read_b128 v[194:197], v160 offset:18432
	ds_read_b128 v[204:207], v160 offset:19456
	ds_read_b128 v[208:211], v160 offset:20480
	ds_read_b128 v[212:215], v160 offset:21504
	ds_read_b128 v[216:219], v160 offset:22528
	ds_read_b128 v[220:223], v160 offset:23552
	global_load_lds_dwordx4 v[156:157], off
	s_add_i32 m0, s94, 0x2000
	v_lshl_add_u64 v[176:177], s[82:83], 0, v[142:143]
	s_add_u32 s82, s82, s48
	s_addc_u32 s83, s83, 0
	s_add_i32 s94, s95, s2
	global_load_lds_dwordx4 v[176:177], off
	v_lshl_add_u64 v[224:225], s[82:83], 0, v[174:175]
	s_mov_b32 m0, s94
	v_lshl_add_u64 v[226:227], s[82:83], 0, v[142:143]
	global_load_lds_dwordx4 v[224:225], off
	s_add_i32 m0, s94, 0x2000
	v_lshl_add_u64 v[228:229], s[54:55], 0, v[138:139]
	global_load_lds_dwordx4 v[226:227], off
	s_mov_b32 m0, s3
	v_lshl_add_u64 v[230:231], s[54:55], 0, v[140:141]
	global_load_lds_dwordx4 v[228:229], off
	s_mov_b32 m0, s12
	s_nop 0
	global_load_lds_dwordx4 v[230:231], off
	s_waitcnt vmcnt(8)
	s_waitcnt lgkmcnt(0)
	s_setprio 1
	s_barrier
; #define PG8_STAGE(bufoff, gbase, voff) do { _Pragma("unroll") for (int _i = 0; _i < 2; ++_i) \
;         __builtin_amdgcn_global_load_lds((const unsigned*)((const char*)(gbase) + (voff)[_i]), (PG8_LAS unsigned*)(lds + (bufoff) + ldsw + _i * 8192), 16, 0, 0); } while (0)
; #define PG8_LDA(dst, b, h) do { _Pragma("unroll") for (int m = 0; m < 4; ++m) _Pragma("unroll") for (int k = 0; k < 2; ++k) dst[m][k] = *(const PG8_LAS bf16x8*)(lds + PG8_SA(b, h) + aoff + m * 2048 + k * 1024); } while (0)
; #define PG8_WAIT_V(n) asm volatile("s_waitcnt vmcnt(" #n ")" ::: "memory")
; #define PG8_WAIT_L(n) asm volatile("s_waitcnt lgkmcnt(" #n ")" ::: "memory")
; #define PG8_BAR __builtin_amdgcn_s_barrier()
; template <class Epi, class Sched, bool ALIGN_EPI = false, bool SP2 = false, bool F16 = false>
; __device__ __forceinline__ void gemm_phase(PG8_LAS unsigned char* lds, const Gemm g, const Sched& S, const Epi& E) {
;     ...
;         for (int t = 0; t < nt; t += 2) {
;             const bool last = (t == nt - 2);
;             const char* a1 = cA + (size_t)(t + 1) * kstep;
;             const char* a2 = last ? nA : cA + (size_t)(t + 2) * kstep; const char* b2 = last ? nB : cB + (size_t)(t + 2) * kstep;
;             const char* a3 = a2 + kstep; const char* b3 = b2 + kstep;
;             if (last && has_next) S.a_ready(nxt);
;             if constexpr (SP2) {
;             PG8_LDB(B0, 0, 0); PG8_LDB(B1, 0, 1); PG8_SCHED; PG8_LDA(At, 0, 0); PG8_STAGE(PG8_SA(1, 1), a1 + hstepA, voffA);
;             PG8_WAIT_V(8); PG8_WAIT_L(0); PG8_BAR; PG8_MMA(0, 0, At, B0); PG8_MMA(0, 1, At, B1); PG8_BAR; PG8_SCHED;
;             PG8_LDA(At, 0, 1); PG8_STAGE(PG8_SB(0, 0), b2, voffB); PG8_STAGE(PG8_SB(0, 1), b2 + hstepB, voffB); PG8_STAGE(PG8_SA(0, 0), a2, voffA);
;             PG8_WAIT_V(8); PG8_WAIT_L(0); PG8_BAR; PG8_MMA(1, 0, At, B0); PG8_MMA(1, 1, At, B1); PG8_BAR; PG8_SCHED;
;             PG8_LDB(B0, 1, 0); PG8_LDB(B1, 1, 1); PG8_SCHED; PG8_LDA(At, 1, 0); PG8_STAGE(PG8_SA(0, 1), a2 + hstepA, voffA);
;             PG8_WAIT_V(8); PG8_WAIT_L(0); PG8_BAR; PG8_MMA(0, 0, At, B0); PG8_MMA(0, 1, At, B1); PG8_BAR; PG8_SCHED;
;             PG8_LDA(At, 1, 1); PG8_STAGE(PG8_SB(1, 0), b3, voffB); PG8_STAGE(PG8_SB(1, 1), b3 + hstepB, voffB); PG8_STAGE(PG8_SA(1, 0), a3, voffA);
;             PG8_WAIT_V(8); PG8_WAIT_L(0); PG8_BAR; PG8_MMA(1, 0, At, B0); PG8_MMA(1, 1, At, B1); PG8_BAR; PG8_SCHED;
	v_mfma_f32_16x16x32_bf16 v[62:65], v[130:133], v[186:189], 0
	v_mfma_f32_16x16x32_bf16 v[58:61], v[148:151], v[186:189], 0
	v_mfma_f32_16x16x32_bf16 v[46:49], v[130:133], v[194:197], 0
	v_mfma_f32_16x16x32_bf16 v[42:45], v[148:151], v[194:197], 0
	v_mfma_f32_16x16x32_bf16 v[30:33], v[130:133], v[208:211], 0
	v_mfma_f32_16x16x32_bf16 v[26:29], v[148:151], v[208:211], 0
	v_mfma_f32_16x16x32_bf16 v[14:17], v[130:133], v[216:219], 0
	v_mfma_f32_16x16x32_bf16 v[10:13], v[148:151], v[216:219], 0
	v_mfma_f32_16x16x32_bf16 v[62:65], v[134:137], v[190:193], v[62:65]
	v_mfma_f32_16x16x32_bf16 v[58:61], v[152:155], v[190:193], v[58:61]
	v_mfma_f32_16x16x32_bf16 v[46:49], v[134:137], v[204:207], v[46:49]
	v_mfma_f32_16x16x32_bf16 v[42:45], v[152:155], v[204:207], v[42:45]
	v_mfma_f32_16x16x32_bf16 v[30:33], v[134:137], v[212:215], v[30:33]
	v_mfma_f32_16x16x32_bf16 v[26:29], v[152:155], v[212:215], v[26:29]
	v_mfma_f32_16x16x32_bf16 v[14:17], v[134:137], v[220:223], v[14:17]
	v_mfma_f32_16x16x32_bf16 v[10:13], v[152:155], v[220:223], v[10:13]
	v_mfma_f32_16x16x32_bf16 v[54:57], v[162:165], v[186:189], 0
	v_mfma_f32_16x16x32_bf16 v[50:53], v[170:173], v[186:189], 0
	v_mfma_f32_16x16x32_bf16 v[38:41], v[162:165], v[194:197], 0
	v_mfma_f32_16x16x32_bf16 v[34:37], v[170:173], v[194:197], 0
	v_mfma_f32_16x16x32_bf16 v[22:25], v[162:165], v[208:211], 0
	v_mfma_f32_16x16x32_bf16 v[18:21], v[170:173], v[208:211], 0
	v_mfma_f32_16x16x32_bf16 v[6:9], v[162:165], v[216:219], 0
	v_mfma_f32_16x16x32_bf16 v[2:5], v[170:173], v[216:219], 0
	v_mfma_f32_16x16x32_bf16 v[54:57], v[166:169], v[190:193], v[54:57]
	v_mfma_f32_16x16x32_bf16 v[50:53], v[182:185], v[190:193], v[50:53]
	v_mfma_f32_16x16x32_bf16 v[38:41], v[166:169], v[204:207], v[38:41]
	v_mfma_f32_16x16x32_bf16 v[34:37], v[182:185], v[204:207], v[34:37]
	v_mfma_f32_16x16x32_bf16 v[22:25], v[166:169], v[212:215], v[22:25]
	v_mfma_f32_16x16x32_bf16 v[18:21], v[182:185], v[212:215], v[18:21]
	v_mfma_f32_16x16x32_bf16 v[6:9], v[166:169], v[220:223], v[6:9]
	v_mfma_f32_16x16x32_bf16 v[2:5], v[182:185], v[220:223], v[2:5]
	s_barrier
	s_setprio 0
	s_add_i32 s82, 0, 0x18000
	s_add_i32 s83, 0, 0x1c000
	v_add_u32_e32 v152, s82, v158
	v_add_u32_e32 v161, s83, v158
	ds_read_b128 v[130:133], v152
	ds_read_b128 v[134:137], v152 offset:1024
	ds_read_b128 v[148:151], v152 offset:2048
	ds_read_b128 v[152:155], v152 offset:3072
	ds_read_b128 v[162:165], v161
	ds_read_b128 v[166:169], v161 offset:1024
	ds_read_b128 v[170:173], v161 offset:2048
	ds_read_b128 v[182:185], v161 offset:3072
	s_add_u32 s54, s54, s8
	s_addc_u32 s55, s55, 0
	s_mov_b32 m0, s13
	v_lshl_add_u64 v[232:233], s[54:55], 0, v[138:139]
	ds_read_b128 v[186:189], v160 offset:32768
	ds_read_b128 v[190:193], v160 offset:33792
	ds_read_b128 v[194:197], v160 offset:34816
	ds_read_b128 v[204:207], v160 offset:35840
	ds_read_b128 v[208:211], v160 offset:36864
	ds_read_b128 v[212:215], v160 offset:37888
	ds_read_b128 v[216:219], v160 offset:38912
	ds_read_b128 v[220:223], v160 offset:39936
	global_load_lds_dwordx4 v[232:233], off
	v_lshl_add_u64 v[232:233], s[54:55], 0, v[140:141]
	s_mov_b32 m0, s22
	s_nop 0
	global_load_lds_dwordx4 v[232:233], off
	s_waitcnt vmcnt(8)
	s_waitcnt lgkmcnt(0)
	s_setprio 1
	s_barrier
	v_mfma_f32_16x16x32_bf16 v[122:125], v[130:133], v[186:189], v[122:125]
	v_mfma_f32_16x16x32_bf16 v[126:129], v[148:151], v[186:189], v[126:129]
	v_mfma_f32_16x16x32_bf16 v[110:113], v[130:133], v[194:197], v[110:113]
	v_mfma_f32_16x16x32_bf16 v[106:109], v[148:151], v[194:197], v[106:109]
	v_mfma_f32_16x16x32_bf16 v[94:97], v[130:133], v[208:211], v[94:97]
	v_mfma_f32_16x16x32_bf16 v[90:93], v[148:151], v[208:211], v[90:93]
	v_mfma_f32_16x16x32_bf16 v[78:81], v[130:133], v[216:219], v[78:81]
	v_mfma_f32_16x16x32_bf16 v[74:77], v[148:151], v[216:219], v[74:77]
	v_mfma_f32_16x16x32_bf16 v[122:125], v[134:137], v[190:193], v[122:125]
	v_mfma_f32_16x16x32_bf16 v[126:129], v[152:155], v[190:193], v[126:129]
	v_mfma_f32_16x16x32_bf16 v[110:113], v[134:137], v[204:207], v[110:113]
	v_mfma_f32_16x16x32_bf16 v[106:109], v[152:155], v[204:207], v[106:109]
	v_mfma_f32_16x16x32_bf16 v[94:97], v[134:137], v[212:215], v[94:97]
	v_mfma_f32_16x16x32_bf16 v[90:93], v[152:155], v[212:215], v[90:93]
	v_mfma_f32_16x16x32_bf16 v[78:81], v[134:137], v[220:223], v[78:81]
	v_mfma_f32_16x16x32_bf16 v[74:77], v[152:155], v[220:223], v[74:77]
	v_mfma_f32_16x16x32_bf16 v[118:121], v[162:165], v[186:189], v[118:121]
	v_mfma_f32_16x16x32_bf16 v[114:117], v[170:173], v[186:189], v[114:117]
	v_mfma_f32_16x16x32_bf16 v[102:105], v[162:165], v[194:197], v[102:105]
	v_mfma_f32_16x16x32_bf16 v[98:101], v[170:173], v[194:197], v[98:101]
	v_mfma_f32_16x16x32_bf16 v[86:89], v[162:165], v[208:211], v[86:89]
	v_mfma_f32_16x16x32_bf16 v[82:85], v[170:173], v[208:211], v[82:85]
	v_mfma_f32_16x16x32_bf16 v[70:73], v[162:165], v[216:219], v[70:73]
	v_mfma_f32_16x16x32_bf16 v[66:69], v[170:173], v[216:219], v[66:69]
	v_mfma_f32_16x16x32_bf16 v[118:121], v[166:169], v[190:193], v[118:121]
	v_mfma_f32_16x16x32_bf16 v[114:117], v[182:185], v[190:193], v[114:117]
	v_mfma_f32_16x16x32_bf16 v[102:105], v[166:169], v[204:207], v[102:105]
	v_mfma_f32_16x16x32_bf16 v[98:101], v[182:185], v[204:207], v[98:101]
	v_mfma_f32_16x16x32_bf16 v[86:89], v[166:169], v[212:215], v[86:89]
	v_mfma_f32_16x16x32_bf16 v[82:85], v[182:185], v[212:215], v[82:85]
	v_mfma_f32_16x16x32_bf16 v[70:73], v[166:169], v[220:223], v[70:73]
	v_mfma_f32_16x16x32_bf16 v[66:69], v[182:185], v[220:223], v[66:69]
	s_barrier
; #define PG8_STAGE(bufoff, gbase, voff) do { _Pragma("unroll") for (int _i = 0; _i < 2; ++_i) \
;         __builtin_amdgcn_global_load_lds((const unsigned*)((const char*)(gbase) + (voff)[_i]), (PG8_LAS unsigned*)(lds + (bufoff) + ldsw + _i * 8192), 16, 0, 0); } while (0)
; #define PG8_LDA(dst, b, h) do { _Pragma("unroll") for (int m = 0; m < 4; ++m) _Pragma("unroll") for (int k = 0; k < 2; ++k) dst[m][k] = *(const PG8_LAS bf16x8*)(lds + PG8_SA(b, h) + aoff + m * 2048 + k * 1024); } while (0)
; #define PG8_WAIT_V(n) asm volatile("s_waitcnt vmcnt(" #n ")" ::: "memory")
; #define PG8_WAIT_L(n) asm volatile("s_waitcnt lgkmcnt(" #n ")" ::: "memory")
; #define PG8_BAR __builtin_amdgcn_s_barrier()
; template <class Epi, class Sched, bool ALIGN_EPI = false, bool SP2 = false, bool F16 = false>
; __device__ __forceinline__ void gemm_phase(PG8_LAS unsigned char* lds, const Gemm g, const Sched& S, const Epi& E) {
;     ...
;         for (int t = 0; t < nt; t += 2) {
;             const bool last = (t == nt - 2);
;             const char* a1 = cA + (size_t)(t + 1) * kstep;
;             const char* a2 = last ? nA : cA + (size_t)(t + 2) * kstep; const char* b2 = last ? nB : cB + (size_t)(t + 2) * kstep;
;             const char* a3 = a2 + kstep; const char* b3 = b2 + kstep;
;             if (last && has_next) S.a_ready(nxt);
;             if constexpr (SP2) {
;             PG8_LDB(B0, 0, 0); PG8_LDB(B1, 0, 1); PG8_SCHED; PG8_LDA(At, 0, 0); PG8_STAGE(PG8_SA(1, 1), a1 + hstepA, voffA);
;             PG8_WAIT_V(8); PG8_WAIT_L(0); PG8_BAR; PG8_MMA(0, 0, At, B0); PG8_MMA(0, 1, At, B1); PG8_BAR; PG8_SCHED;
;             PG8_LDA(At, 0, 1); PG8_STAGE(PG8_SB(0, 0), b2, voffB); PG8_STAGE(PG8_SB(0, 1), b2 + hstepB, voffB); PG8_STAGE(PG8_SA(0, 0), a2, voffA);
;             PG8_WAIT_V(8); PG8_WAIT_L(0); PG8_BAR; PG8_MMA(1, 0, At, B0); PG8_MMA(1, 1, At, B1); PG8_BAR; PG8_SCHED;
;             PG8_LDB(B0, 1, 0); PG8_LDB(B1, 1, 1); PG8_SCHED; PG8_LDA(At, 1, 0); PG8_STAGE(PG8_SA(0, 1), a2 + hstepA, voffA);
;             PG8_WAIT_V(8); PG8_WAIT_L(0); PG8_BAR; PG8_MMA(0, 0, At, B0); PG8_MMA(0, 1, At, B1); PG8_BAR; PG8_SCHED;
;             PG8_LDA(At, 1, 1); PG8_STAGE(PG8_SB(1, 0), b3, voffB); PG8_STAGE(PG8_SB(1, 1), b3 + hstepB, voffB); PG8_STAGE(PG8_SA(1, 0), a3, voffA);
;             PG8_WAIT_V(8); PG8_WAIT_L(0); PG8_BAR; PG8_MMA(1, 0, At, B0); PG8_MMA(1, 1, At, B1); PG8_BAR; PG8_SCHED;
	s_setprio 0
	s_add_i32 s54, s82, s2
	v_lshl_add_u64 v[156:157], v[156:157], 0, s[92:93]
	s_mov_b32 m0, s54
	ds_read_b128 v[186:189], v160 offset:49152
	ds_read_b128 v[190:193], v160 offset:50176
	ds_read_b128 v[194:197], v160 offset:51200
	ds_read_b128 v[204:207], v160 offset:52224
	ds_read_b128 v[208:211], v160 offset:53248
	ds_read_b128 v[212:215], v160 offset:54272
	ds_read_b128 v[216:219], v160 offset:55296
	ds_read_b128 v[220:223], v160 offset:56320
	global_load_lds_dwordx4 v[156:157], off
	v_lshl_add_u64 v[156:157], v[176:177], 0, s[92:93]
	s_add_i32 m0, s54, 0x2000
	s_add_i32 s54, s83, s2
	global_load_lds_dwordx4 v[156:157], off
	v_lshl_add_u64 v[156:157], v[224:225], 0, s[92:93]
	s_mov_b32 m0, s54
	s_nop 0
	global_load_lds_dwordx4 v[156:157], off
	v_lshl_add_u64 v[156:157], v[226:227], 0, s[92:93]
	s_add_i32 m0, s54, 0x2000
	s_nop 0
	global_load_lds_dwordx4 v[156:157], off
	v_lshl_add_u64 v[156:157], v[228:229], 0, s[92:93]
	s_mov_b32 m0, s33
	s_nop 0
	global_load_lds_dwordx4 v[156:157], off
	v_lshl_add_u64 v[156:157], v[230:231], 0, s[92:93]
	s_mov_b32 m0, s35
	s_nop 0
	global_load_lds_dwordx4 v[156:157], off
	s_waitcnt vmcnt(8)
	s_waitcnt lgkmcnt(0)
	s_setprio 1
	s_barrier
	v_mfma_f32_16x16x32_bf16 v[62:65], v[130:133], v[186:189], v[62:65]
	v_mfma_f32_16x16x32_bf16 v[58:61], v[148:151], v[186:189], v[58:61]
	v_mfma_f32_16x16x32_bf16 v[46:49], v[130:133], v[194:197], v[46:49]
	v_mfma_f32_16x16x32_bf16 v[42:45], v[148:151], v[194:197], v[42:45]
	v_mfma_f32_16x16x32_bf16 v[30:33], v[130:133], v[208:211], v[30:33]
	v_mfma_f32_16x16x32_bf16 v[26:29], v[148:151], v[208:211], v[26:29]
	v_mfma_f32_16x16x32_bf16 v[14:17], v[130:133], v[216:219], v[14:17]
	v_mfma_f32_16x16x32_bf16 v[10:13], v[148:151], v[216:219], v[10:13]
	v_mfma_f32_16x16x32_bf16 v[62:65], v[134:137], v[190:193], v[62:65]
	v_mfma_f32_16x16x32_bf16 v[58:61], v[152:155], v[190:193], v[58:61]
	v_mfma_f32_16x16x32_bf16 v[46:49], v[134:137], v[204:207], v[46:49]
	v_mfma_f32_16x16x32_bf16 v[42:45], v[152:155], v[204:207], v[42:45]
	v_mfma_f32_16x16x32_bf16 v[30:33], v[134:137], v[212:215], v[30:33]
	v_mfma_f32_16x16x32_bf16 v[26:29], v[152:155], v[212:215], v[26:29]
	v_mfma_f32_16x16x32_bf16 v[14:17], v[134:137], v[220:223], v[14:17]
	v_mfma_f32_16x16x32_bf16 v[10:13], v[152:155], v[220:223], v[10:13]
	v_mfma_f32_16x16x32_bf16 v[54:57], v[162:165], v[186:189], v[54:57]
	v_mfma_f32_16x16x32_bf16 v[50:53], v[170:173], v[186:189], v[50:53]
	v_mfma_f32_16x16x32_bf16 v[38:41], v[162:165], v[194:197], v[38:41]
	v_mfma_f32_16x16x32_bf16 v[34:37], v[170:173], v[194:197], v[34:37]
	v_mfma_f32_16x16x32_bf16 v[22:25], v[162:165], v[208:211], v[22:25]
	v_mfma_f32_16x16x32_bf16 v[18:21], v[170:173], v[208:211], v[18:21]
	v_mfma_f32_16x16x32_bf16 v[6:9], v[162:165], v[216:219], v[6:9]
	v_mfma_f32_16x16x32_bf16 v[2:5], v[170:173], v[216:219], v[2:5]
	v_mfma_f32_16x16x32_bf16 v[54:57], v[166:169], v[190:193], v[54:57]
	v_mfma_f32_16x16x32_bf16 v[50:53], v[182:185], v[190:193], v[50:53]
	v_mfma_f32_16x16x32_bf16 v[38:41], v[166:169], v[204:207], v[38:41]
	v_mfma_f32_16x16x32_bf16 v[34:37], v[182:185], v[204:207], v[34:37]
	v_mfma_f32_16x16x32_bf16 v[22:25], v[166:169], v[212:215], v[22:25]
	v_mfma_f32_16x16x32_bf16 v[18:21], v[182:185], v[212:215], v[18:21]
	v_mfma_f32_16x16x32_bf16 v[6:9], v[166:169], v[220:223], v[6:9]
	v_mfma_f32_16x16x32_bf16 v[2:5], v[182:185], v[220:223], v[2:5]
	s_barrier
	s_setprio 0
	s_add_u32 s52, s52, 0x100
	s_addc_u32 s53, s53, 0
	s_add_u32 s79, s79, 0x100
	s_addc_u32 s80, s80, 0
	s_cmp_ge_u32 s81, s65
	s_mov_b32 s54, s81
	s_cbranch_scc1 .LBB0_346

; #define PG8_STAGE(bufoff, gbase, voff) do { _Pragma("unroll") for (int _i = 0; _i < 2; ++_i) \
;         __builtin_amdgcn_global_load_lds((const unsigned*)((const char*)(gbase) + (voff)[_i]), (PG8_LAS unsigned*)(lds + (bufoff) + ldsw + _i * 8192), 16, 0, 0); } while (0)
; #define PG8_LDA(dst, b, h) do { _Pragma("unroll") for (int m = 0; m < 4; ++m) _Pragma("unroll") for (int k = 0; k < 2; ++k) dst[m][k] = *(const PG8_LAS bf16x8*)(lds + PG8_SA(b, h) + aoff + m * 2048 + k * 1024); } while (0)
; #define PG8_WAIT_V(n) asm volatile("s_waitcnt vmcnt(" #n ")" ::: "memory")
; #define PG8_WAIT_L(n) asm volatile("s_waitcnt lgkmcnt(" #n ")" ::: "memory")
; #define PG8_BAR __builtin_amdgcn_s_barrier()
; template <class Epi, class Sched, bool ALIGN_EPI = false, bool SP2 = false, bool F16 = false>
; __device__ __forceinline__ void gemm_phase(PG8_LAS unsigned char* lds, const Gemm g, const Sched& S, const Epi& E) {
;     ...
;         for (int t = 0; t < nt; t += 2) {
;             const bool last = (t == nt - 2);
;             const char* a1 = cA + (size_t)(t + 1) * kstep;
;             const char* a2 = last ? nA : cA + (size_t)(t + 2) * kstep; const char* b2 = last ? nB : cB + (size_t)(t + 2) * kstep;
;             const char* a3 = a2 + kstep; const char* b3 = b2 + kstep;
;             if (last && has_next) S.a_ready(nxt);
;             if constexpr (SP2) {
;             PG8_LDB(B0, 0, 0); PG8_LDB(B1, 0, 1); PG8_SCHED; PG8_LDA(At, 0, 0); PG8_STAGE(PG8_SA(1, 1), a1 + hstepA, voffA);
;             PG8_WAIT_V(8); PG8_WAIT_L(0); PG8_BAR; PG8_MMA(0, 0, At, B0); PG8_MMA(0, 1, At, B1); PG8_BAR; PG8_SCHED;
;             PG8_LDA(At, 0, 1); PG8_STAGE(PG8_SB(0, 0), b2, voffB); PG8_STAGE(PG8_SB(0, 1), b2 + hstepB, voffB); PG8_STAGE(PG8_SA(0, 0), a2, voffA);
;             PG8_WAIT_V(8); PG8_WAIT_L(0); PG8_BAR; PG8_MMA(1, 0, At, B0); PG8_MMA(1, 1, At, B1); PG8_BAR; PG8_SCHED;
;             PG8_LDB(B0, 1, 0); PG8_LDB(B1, 1, 1); PG8_SCHED; PG8_LDA(At, 1, 0); PG8_STAGE(PG8_SA(0, 1), a2 + hstepA, voffA);
;             PG8_WAIT_V(8); PG8_WAIT_L(0); PG8_BAR; PG8_MMA(0, 0, At, B0); PG8_MMA(0, 1, At, B1); PG8_BAR; PG8_SCHED;
;             PG8_LDA(At, 1, 1); PG8_STAGE(PG8_SB(1, 0), b3, voffB); PG8_STAGE(PG8_SB(1, 1), b3 + hstepB, voffB); PG8_STAGE(PG8_SA(1, 0), a3, voffA);
;             PG8_WAIT_V(8); PG8_WAIT_L(0); PG8_BAR; PG8_MMA(1, 0, At, B0); PG8_MMA(1, 1, At, B1); PG8_BAR; PG8_SCHED;
.LBB0_396:
	s_andn2_b64 vcc, exec, s[4:5]
	s_waitcnt vmcnt(0)
	s_cbranch_vccnz .Lzk_bf
	s_add_u32 s46, s78, 0x80
	s_addc_u32 s47, s79, 0
	s_add_u32 s13, s72, 0x100
	s_addc_u32 s24, s73, 0
	s_mov_b32 s72, 0
.Lpk_bf:
	s_add_i32 s78, s72, 2
	s_add_u32 s79, s46, 0x80
	s_addc_u32 s73, s47, 0
	s_add_i32 vcc_lo, 0, 0x10000
	s_cmp_eq_u32 s74, s72
	s_cselect_b32 s73, s55, s73
	s_cselect_b32 s72, s54, s79
	s_cselect_b32 s95, s53, s24
	s_cselect_b32 s94, s52, s13
	s_add_i32 s79, 0, 0x14000
	v_add_u32_e32 v142, vcc_lo, v163
	v_add_u32_e32 v172, s79, v163
	ds_read_b128 v[130:133], v142
	ds_read_b128 v[134:137], v142 offset:1024
	ds_read_b128 v[138:141], v142 offset:2048
	ds_read_b128 v[142:145], v142 offset:3072
	ds_read_b128 v[146:149], v172
	ds_read_b128 v[150:153], v172 offset:1024
	ds_read_b128 v[182:185], v172 offset:2048
	ds_read_b128 v[186:189], v172 offset:3072
	v_lshl_add_u64 v[172:173], s[46:47], 0, v[168:169]
	s_add_i32 m0, s36, 0xc000
	ds_read_b128 v[190:193], v204
	ds_read_b128 v[194:197], v204 offset:1024
	ds_read_b128 v[206:209], v204 offset:2048
	ds_read_b128 v[210:213], v204 offset:3072
	ds_read_b128 v[214:217], v204 offset:4096
	ds_read_b128 v[218:221], v204 offset:5120
	ds_read_b128 v[222:225], v204 offset:6144
	ds_read_b128 v[226:229], v204 offset:7168
	global_load_lds_dwordx4 v[172:173], off
	v_lshl_add_u64 v[172:173], s[46:47], 0, v[170:171]
	s_add_i32 m0, s36, 0xe000
	s_nop 0
	global_load_lds_dwordx4 v[172:173], off
	s_waitcnt vmcnt(8)
	s_waitcnt lgkmcnt(0)
	s_setprio 1
	s_barrier
	v_mfma_f32_16x16x32_bf16 v[122:125], v[130:133], v[190:193], 0
	v_mfma_f32_16x16x32_bf16 v[126:129], v[138:141], v[190:193], 0
	v_mfma_f32_16x16x32_bf16 v[110:113], v[130:133], v[206:209], 0
	v_mfma_f32_16x16x32_bf16 v[106:109], v[138:141], v[206:209], 0
	v_mfma_f32_16x16x32_bf16 v[94:97], v[130:133], v[214:217], 0
	v_mfma_f32_16x16x32_bf16 v[90:93], v[138:141], v[214:217], 0
	v_mfma_f32_16x16x32_bf16 v[78:81], v[130:133], v[222:225], 0
	v_mfma_f32_16x16x32_bf16 v[74:77], v[138:141], v[222:225], 0
	v_mfma_f32_16x16x32_bf16 v[122:125], v[134:137], v[194:197], v[122:125]
	v_mfma_f32_16x16x32_bf16 v[126:129], v[142:145], v[194:197], v[126:129]
	v_mfma_f32_16x16x32_bf16 v[110:113], v[134:137], v[210:213], v[110:113]
	v_mfma_f32_16x16x32_bf16 v[106:109], v[142:145], v[210:213], v[106:109]
	v_mfma_f32_16x16x32_bf16 v[94:97], v[134:137], v[218:221], v[94:97]
	v_mfma_f32_16x16x32_bf16 v[90:93], v[142:145], v[218:221], v[90:93]
	v_mfma_f32_16x16x32_bf16 v[78:81], v[134:137], v[226:229], v[78:81]
	v_mfma_f32_16x16x32_bf16 v[74:77], v[142:145], v[226:229], v[74:77]
	v_mfma_f32_16x16x32_bf16 v[118:121], v[146:149], v[190:193], 0
	v_mfma_f32_16x16x32_bf16 v[114:117], v[182:185], v[190:193], 0
	v_mfma_f32_16x16x32_bf16 v[102:105], v[146:149], v[206:209], 0
	v_mfma_f32_16x16x32_bf16 v[98:101], v[182:185], v[206:209], 0
	v_mfma_f32_16x16x32_bf16 v[86:89], v[146:149], v[214:217], 0
	v_mfma_f32_16x16x32_bf16 v[82:85], v[182:185], v[214:217], 0
	v_mfma_f32_16x16x32_bf16 v[70:73], v[146:149], v[222:225], 0
	v_mfma_f32_16x16x32_bf16 v[66:69], v[182:185], v[222:225], 0
	v_mfma_f32_16x16x32_bf16 v[118:121], v[150:153], v[194:197], v[118:121]
	v_mfma_f32_16x16x32_bf16 v[114:117], v[186:189], v[194:197], v[114:117]
	v_mfma_f32_16x16x32_bf16 v[102:105], v[150:153], v[210:213], v[102:105]
	v_mfma_f32_16x16x32_bf16 v[98:101], v[186:189], v[210:213], v[98:101]
	v_mfma_f32_16x16x32_bf16 v[86:89], v[150:153], v[218:221], v[86:89]
	v_mfma_f32_16x16x32_bf16 v[82:85], v[186:189], v[218:221], v[82:85]
	v_mfma_f32_16x16x32_bf16 v[70:73], v[150:153], v[226:229], v[70:73]
	v_mfma_f32_16x16x32_bf16 v[66:69], v[186:189], v[226:229], v[66:69]
	s_barrier
	s_setprio 0
	s_add_i32 vcc_lo, vcc_lo, s75
	v_lshl_add_u64 v[172:173], s[94:95], 0, v[156:157]
	s_mov_b32 m0, vcc_lo
	ds_read_b128 v[190:193], v204 offset:16384
	ds_read_b128 v[194:197], v204 offset:17408
	ds_read_b128 v[206:209], v204 offset:18432
	ds_read_b128 v[210:213], v204 offset:19456
	ds_read_b128 v[214:217], v204 offset:20480
	ds_read_b128 v[218:221], v204 offset:21504
	ds_read_b128 v[222:225], v204 offset:22528
	ds_read_b128 v[226:229], v204 offset:23552
	global_load_lds_dwordx4 v[172:173], off
	s_add_i32 m0, vcc_lo, 0x2000
	v_lshl_add_u64 v[176:177], s[94:95], 0, v[160:161]
	s_add_u32 s94, s94, s48
	s_addc_u32 s95, s95, 0
	s_add_i32 s79, s79, s75
	global_load_lds_dwordx4 v[176:177], off
	v_lshl_add_u64 v[230:231], s[94:95], 0, v[156:157]
	s_mov_b32 m0, s79
	v_lshl_add_u64 v[232:233], s[94:95], 0, v[160:161]
	global_load_lds_dwordx4 v[230:231], off
	s_add_i32 m0, s79, 0x2000
	v_lshl_add_u64 v[234:235], s[72:73], 0, v[154:155]
	global_load_lds_dwordx4 v[232:233], off
	s_mov_b32 m0, s36
	v_lshl_add_u64 v[236:237], s[72:73], 0, v[158:159]
	global_load_lds_dwordx4 v[234:235], off
	s_mov_b32 m0, s37
	s_nop 0
	global_load_lds_dwordx4 v[236:237], off
	s_waitcnt vmcnt(8)
	s_waitcnt lgkmcnt(0)
	s_setprio 1
	s_barrier
; #define PG8_STAGE(bufoff, gbase, voff) do { _Pragma("unroll") for (int _i = 0; _i < 2; ++_i) \
;         __builtin_amdgcn_global_load_lds((const unsigned*)((const char*)(gbase) + (voff)[_i]), (PG8_LAS unsigned*)(lds + (bufoff) + ldsw + _i * 8192), 16, 0, 0); } while (0)
; #define PG8_LDA(dst, b, h) do { _Pragma("unroll") for (int m = 0; m < 4; ++m) _Pragma("unroll") for (int k = 0; k < 2; ++k) dst[m][k] = *(const PG8_LAS bf16x8*)(lds + PG8_SA(b, h) + aoff + m * 2048 + k * 1024); } while (0)
; #define PG8_WAIT_V(n) asm volatile("s_waitcnt vmcnt(" #n ")" ::: "memory")
; #define PG8_WAIT_L(n) asm volatile("s_waitcnt lgkmcnt(" #n ")" ::: "memory")
; #define PG8_BAR __builtin_amdgcn_s_barrier()
; template <class Epi, class Sched, bool ALIGN_EPI = false, bool SP2 = false, bool F16 = false>
; __device__ __forceinline__ void gemm_phase(PG8_LAS unsigned char* lds, const Gemm g, const Sched& S, const Epi& E) {
;     ...
;         for (int t = 0; t < nt; t += 2) {
;             const bool last = (t == nt - 2);
;             const char* a1 = cA + (size_t)(t + 1) * kstep;
;             const char* a2 = last ? nA : cA + (size_t)(t + 2) * kstep; const char* b2 = last ? nB : cB + (size_t)(t + 2) * kstep;
;             const char* a3 = a2 + kstep; const char* b3 = b2 + kstep;
;             if (last && has_next) S.a_ready(nxt);
;             if constexpr (SP2) {
;             PG8_LDB(B0, 0, 0); PG8_LDB(B1, 0, 1); PG8_SCHED; PG8_LDA(At, 0, 0); PG8_STAGE(PG8_SA(1, 1), a1 + hstepA, voffA);
;             PG8_WAIT_V(8); PG8_WAIT_L(0); PG8_BAR; PG8_MMA(0, 0, At, B0); PG8_MMA(0, 1, At, B1); PG8_BAR; PG8_SCHED;
;             PG8_LDA(At, 0, 1); PG8_STAGE(PG8_SB(0, 0), b2, voffB); PG8_STAGE(PG8_SB(0, 1), b2 + hstepB, voffB); PG8_STAGE(PG8_SA(0, 0), a2, voffA);
;             PG8_WAIT_V(8); PG8_WAIT_L(0); PG8_BAR; PG8_MMA(1, 0, At, B0); PG8_MMA(1, 1, At, B1); PG8_BAR; PG8_SCHED;
;             PG8_LDB(B0, 1, 0); PG8_LDB(B1, 1, 1); PG8_SCHED; PG8_LDA(At, 1, 0); PG8_STAGE(PG8_SA(0, 1), a2 + hstepA, voffA);
;             PG8_WAIT_V(8); PG8_WAIT_L(0); PG8_BAR; PG8_MMA(0, 0, At, B0); PG8_MMA(0, 1, At, B1); PG8_BAR; PG8_SCHED;
;             PG8_LDA(At, 1, 1); PG8_STAGE(PG8_SB(1, 0), b3, voffB); PG8_STAGE(PG8_SB(1, 1), b3 + hstepB, voffB); PG8_STAGE(PG8_SA(1, 0), a3, voffA);
;             PG8_WAIT_V(8); PG8_WAIT_L(0); PG8_BAR; PG8_MMA(1, 0, At, B0); PG8_MMA(1, 1, At, B1); PG8_BAR; PG8_SCHED;
	v_mfma_f32_16x16x32_bf16 v[62:65], v[130:133], v[190:193], 0
	v_mfma_f32_16x16x32_bf16 v[58:61], v[138:141], v[190:193], 0
	v_mfma_f32_16x16x32_bf16 v[46:49], v[130:133], v[206:209], 0
	v_mfma_f32_16x16x32_bf16 v[42:45], v[138:141], v[206:209], 0
	v_mfma_f32_16x16x32_bf16 v[30:33], v[130:133], v[214:217], 0
	v_mfma_f32_16x16x32_bf16 v[26:29], v[138:141], v[214:217], 0
	v_mfma_f32_16x16x32_bf16 v[14:17], v[130:133], v[222:225], 0
	v_mfma_f32_16x16x32_bf16 v[10:13], v[138:141], v[222:225], 0
	v_mfma_f32_16x16x32_bf16 v[62:65], v[134:137], v[194:197], v[62:65]
	v_mfma_f32_16x16x32_bf16 v[58:61], v[142:145], v[194:197], v[58:61]
	v_mfma_f32_16x16x32_bf16 v[46:49], v[134:137], v[210:213], v[46:49]
	v_mfma_f32_16x16x32_bf16 v[42:45], v[142:145], v[210:213], v[42:45]
	v_mfma_f32_16x16x32_bf16 v[30:33], v[134:137], v[218:221], v[30:33]
	v_mfma_f32_16x16x32_bf16 v[26:29], v[142:145], v[218:221], v[26:29]
	v_mfma_f32_16x16x32_bf16 v[14:17], v[134:137], v[226:229], v[14:17]
	v_mfma_f32_16x16x32_bf16 v[10:13], v[142:145], v[226:229], v[10:13]
	v_mfma_f32_16x16x32_bf16 v[54:57], v[146:149], v[190:193], 0
	v_mfma_f32_16x16x32_bf16 v[50:53], v[182:185], v[190:193], 0
	v_mfma_f32_16x16x32_bf16 v[38:41], v[146:149], v[206:209], 0
	v_mfma_f32_16x16x32_bf16 v[34:37], v[182:185], v[206:209], 0
	v_mfma_f32_16x16x32_bf16 v[22:25], v[146:149], v[214:217], 0
	v_mfma_f32_16x16x32_bf16 v[18:21], v[182:185], v[214:217], 0
	v_mfma_f32_16x16x32_bf16 v[6:9], v[146:149], v[222:225], 0
	v_mfma_f32_16x16x32_bf16 v[2:5], v[182:185], v[222:225], 0
	v_mfma_f32_16x16x32_bf16 v[54:57], v[150:153], v[194:197], v[54:57]
	v_mfma_f32_16x16x32_bf16 v[50:53], v[186:189], v[194:197], v[50:53]
	v_mfma_f32_16x16x32_bf16 v[38:41], v[150:153], v[210:213], v[38:41]
	v_mfma_f32_16x16x32_bf16 v[34:37], v[186:189], v[210:213], v[34:37]
	v_mfma_f32_16x16x32_bf16 v[22:25], v[150:153], v[218:221], v[22:25]
	v_mfma_f32_16x16x32_bf16 v[18:21], v[186:189], v[218:221], v[18:21]
	v_mfma_f32_16x16x32_bf16 v[6:9], v[150:153], v[226:229], v[6:9]
	v_mfma_f32_16x16x32_bf16 v[2:5], v[186:189], v[226:229], v[2:5]
	s_barrier
	s_setprio 0
	s_add_i32 s79, 0, 0x18000
	s_add_i32 s94, 0, 0x1c000
	v_add_u32_e32 v142, s79, v163
	v_add_u32_e32 v174, s94, v163
	ds_read_b128 v[130:133], v142
	ds_read_b128 v[134:137], v142 offset:1024
	ds_read_b128 v[138:141], v142 offset:2048
	ds_read_b128 v[142:145], v142 offset:3072
	ds_read_b128 v[146:149], v174
	ds_read_b128 v[150:153], v174 offset:1024
	ds_read_b128 v[182:185], v174 offset:2048
	ds_read_b128 v[186:189], v174 offset:3072
	s_add_u32 s72, s72, s8
	s_addc_u32 s73, s73, 0
	s_mov_b32 m0, s35
	v_lshl_add_u64 v[238:239], s[72:73], 0, v[154:155]
	ds_read_b128 v[190:193], v204 offset:32768
	ds_read_b128 v[194:197], v204 offset:33792
	ds_read_b128 v[206:209], v204 offset:34816
	ds_read_b128 v[210:213], v204 offset:35840
	ds_read_b128 v[214:217], v204 offset:36864
	ds_read_b128 v[218:221], v204 offset:37888
	ds_read_b128 v[222:225], v204 offset:38912
	ds_read_b128 v[226:229], v204 offset:39936
	global_load_lds_dwordx4 v[238:239], off
	v_lshl_add_u64 v[238:239], s[72:73], 0, v[158:159]
	s_mov_b32 m0, s2
	s_nop 0
	global_load_lds_dwordx4 v[238:239], off
	s_waitcnt vmcnt(8)
	s_waitcnt lgkmcnt(0)
	s_setprio 1
	s_barrier
	v_mfma_f32_16x16x32_bf16 v[122:125], v[130:133], v[190:193], v[122:125]
	v_mfma_f32_16x16x32_bf16 v[126:129], v[138:141], v[190:193], v[126:129]
	v_mfma_f32_16x16x32_bf16 v[110:113], v[130:133], v[206:209], v[110:113]
	v_mfma_f32_16x16x32_bf16 v[106:109], v[138:141], v[206:209], v[106:109]
	v_mfma_f32_16x16x32_bf16 v[94:97], v[130:133], v[214:217], v[94:97]
	v_mfma_f32_16x16x32_bf16 v[90:93], v[138:141], v[214:217], v[90:93]
	v_mfma_f32_16x16x32_bf16 v[78:81], v[130:133], v[222:225], v[78:81]
	v_mfma_f32_16x16x32_bf16 v[74:77], v[138:141], v[222:225], v[74:77]
	v_mfma_f32_16x16x32_bf16 v[122:125], v[134:137], v[194:197], v[122:125]
	v_mfma_f32_16x16x32_bf16 v[126:129], v[142:145], v[194:197], v[126:129]
	v_mfma_f32_16x16x32_bf16 v[110:113], v[134:137], v[210:213], v[110:113]
	v_mfma_f32_16x16x32_bf16 v[106:109], v[142:145], v[210:213], v[106:109]
	v_mfma_f32_16x16x32_bf16 v[94:97], v[134:137], v[218:221], v[94:97]
	v_mfma_f32_16x16x32_bf16 v[90:93], v[142:145], v[218:221], v[90:93]
	v_mfma_f32_16x16x32_bf16 v[78:81], v[134:137], v[226:229], v[78:81]
	v_mfma_f32_16x16x32_bf16 v[74:77], v[142:145], v[226:229], v[74:77]
	v_mfma_f32_16x16x32_bf16 v[118:121], v[146:149], v[190:193], v[118:121]
	v_mfma_f32_16x16x32_bf16 v[114:117], v[182:185], v[190:193], v[114:117]
	v_mfma_f32_16x16x32_bf16 v[102:105], v[146:149], v[206:209], v[102:105]
	v_mfma_f32_16x16x32_bf16 v[98:101], v[182:185], v[206:209], v[98:101]
	v_mfma_f32_16x16x32_bf16 v[86:89], v[146:149], v[214:217], v[86:89]
	v_mfma_f32_16x16x32_bf16 v[82:85], v[182:185], v[214:217], v[82:85]
	v_mfma_f32_16x16x32_bf16 v[70:73], v[146:149], v[222:225], v[70:73]
	v_mfma_f32_16x16x32_bf16 v[66:69], v[182:185], v[222:225], v[66:69]
	v_mfma_f32_16x16x32_bf16 v[118:121], v[150:153], v[194:197], v[118:121]
	v_mfma_f32_16x16x32_bf16 v[114:117], v[186:189], v[194:197], v[114:117]
	v_mfma_f32_16x16x32_bf16 v[102:105], v[150:153], v[210:213], v[102:105]
	v_mfma_f32_16x16x32_bf16 v[98:101], v[186:189], v[210:213], v[98:101]
	v_mfma_f32_16x16x32_bf16 v[86:89], v[150:153], v[218:221], v[86:89]
	v_mfma_f32_16x16x32_bf16 v[82:85], v[186:189], v[218:221], v[82:85]
	v_mfma_f32_16x16x32_bf16 v[70:73], v[150:153], v[226:229], v[70:73]
	v_mfma_f32_16x16x32_bf16 v[66:69], v[186:189], v[226:229], v[66:69]
	s_barrier
; #define PG8_STAGE(bufoff, gbase, voff) do { _Pragma("unroll") for (int _i = 0; _i < 2; ++_i) \
;         __builtin_amdgcn_global_load_lds((const unsigned*)((const char*)(gbase) + (voff)[_i]), (PG8_LAS unsigned*)(lds + (bufoff) + ldsw + _i * 8192), 16, 0, 0); } while (0)
; #define PG8_LDA(dst, b, h) do { _Pragma("unroll") for (int m = 0; m < 4; ++m) _Pragma("unroll") for (int k = 0; k < 2; ++k) dst[m][k] = *(const PG8_LAS bf16x8*)(lds + PG8_SA(b, h) + aoff + m * 2048 + k * 1024); } while (0)
; #define PG8_WAIT_V(n) asm volatile("s_waitcnt vmcnt(" #n ")" ::: "memory")
; #define PG8_WAIT_L(n) asm volatile("s_waitcnt lgkmcnt(" #n ")" ::: "memory")
; #define PG8_BAR __builtin_amdgcn_s_barrier()
; template <class Epi, class Sched, bool ALIGN_EPI = false, bool SP2 = false, bool F16 = false>
; __device__ __forceinline__ void gemm_phase(PG8_LAS unsigned char* lds, const Gemm g, const Sched& S, const Epi& E) {
;     ...
;         for (int t = 0; t < nt; t += 2) {
;             const bool last = (t == nt - 2);
;             const char* a1 = cA + (size_t)(t + 1) * kstep;
;             const char* a2 = last ? nA : cA + (size_t)(t + 2) * kstep; const char* b2 = last ? nB : cB + (size_t)(t + 2) * kstep;
;             const char* a3 = a2 + kstep; const char* b3 = b2 + kstep;
;             if (last && has_next) S.a_ready(nxt);
;             if constexpr (SP2) {
;             PG8_LDB(B0, 0, 0); PG8_LDB(B1, 0, 1); PG8_SCHED; PG8_LDA(At, 0, 0); PG8_STAGE(PG8_SA(1, 1), a1 + hstepA, voffA);
;             PG8_WAIT_V(8); PG8_WAIT_L(0); PG8_BAR; PG8_MMA(0, 0, At, B0); PG8_MMA(0, 1, At, B1); PG8_BAR; PG8_SCHED;
;             PG8_LDA(At, 0, 1); PG8_STAGE(PG8_SB(0, 0), b2, voffB); PG8_STAGE(PG8_SB(0, 1), b2 + hstepB, voffB); PG8_STAGE(PG8_SA(0, 0), a2, voffA);
;             PG8_WAIT_V(8); PG8_WAIT_L(0); PG8_BAR; PG8_MMA(1, 0, At, B0); PG8_MMA(1, 1, At, B1); PG8_BAR; PG8_SCHED;
;             PG8_LDB(B0, 1, 0); PG8_LDB(B1, 1, 1); PG8_SCHED; PG8_LDA(At, 1, 0); PG8_STAGE(PG8_SA(0, 1), a2 + hstepA, voffA);
;             PG8_WAIT_V(8); PG8_WAIT_L(0); PG8_BAR; PG8_MMA(0, 0, At, B0); PG8_MMA(0, 1, At, B1); PG8_BAR; PG8_SCHED;
;             PG8_LDA(At, 1, 1); PG8_STAGE(PG8_SB(1, 0), b3, voffB); PG8_STAGE(PG8_SB(1, 1), b3 + hstepB, voffB); PG8_STAGE(PG8_SA(1, 0), a3, voffA);
;             PG8_WAIT_V(8); PG8_WAIT_L(0); PG8_BAR; PG8_MMA(1, 0, At, B0); PG8_MMA(1, 1, At, B1); PG8_BAR; PG8_SCHED;
	s_setprio 0
	s_add_i32 s72, s79, s75
	v_lshl_add_u64 v[172:173], v[172:173], 0, s[92:93]
	s_mov_b32 m0, s72
	ds_read_b128 v[190:193], v204 offset:49152
	ds_read_b128 v[194:197], v204 offset:50176
	ds_read_b128 v[206:209], v204 offset:51200
	ds_read_b128 v[210:213], v204 offset:52224
	ds_read_b128 v[214:217], v204 offset:53248
	ds_read_b128 v[218:221], v204 offset:54272
	ds_read_b128 v[222:225], v204 offset:55296
	ds_read_b128 v[226:229], v204 offset:56320
	global_load_lds_dwordx4 v[172:173], off
	v_lshl_add_u64 v[172:173], v[176:177], 0, s[92:93]
	s_add_i32 m0, s72, 0x2000
	s_add_i32 s72, s94, s75
	global_load_lds_dwordx4 v[172:173], off
	v_lshl_add_u64 v[172:173], v[230:231], 0, s[92:93]
	s_mov_b32 m0, s72
	s_nop 0
	global_load_lds_dwordx4 v[172:173], off
	v_lshl_add_u64 v[172:173], v[232:233], 0, s[92:93]
	s_add_i32 m0, s72, 0x2000
	s_nop 0
	global_load_lds_dwordx4 v[172:173], off
	v_lshl_add_u64 v[172:173], v[234:235], 0, s[92:93]
	s_mov_b32 m0, s22
	s_nop 0
	global_load_lds_dwordx4 v[172:173], off
	v_lshl_add_u64 v[172:173], v[236:237], 0, s[92:93]
	s_mov_b32 m0, s23
	s_nop 0
	global_load_lds_dwordx4 v[172:173], off
	s_waitcnt vmcnt(8)
	s_waitcnt lgkmcnt(0)
	s_setprio 1
	s_barrier
	v_mfma_f32_16x16x32_bf16 v[62:65], v[130:133], v[190:193], v[62:65]
	v_mfma_f32_16x16x32_bf16 v[58:61], v[138:141], v[190:193], v[58:61]
	v_mfma_f32_16x16x32_bf16 v[46:49], v[130:133], v[206:209], v[46:49]
	v_mfma_f32_16x16x32_bf16 v[42:45], v[138:141], v[206:209], v[42:45]
	v_mfma_f32_16x16x32_bf16 v[30:33], v[130:133], v[214:217], v[30:33]
	v_mfma_f32_16x16x32_bf16 v[26:29], v[138:141], v[214:217], v[26:29]
	v_mfma_f32_16x16x32_bf16 v[14:17], v[130:133], v[222:225], v[14:17]
	v_mfma_f32_16x16x32_bf16 v[10:13], v[138:141], v[222:225], v[10:13]
	v_mfma_f32_16x16x32_bf16 v[62:65], v[134:137], v[194:197], v[62:65]
	v_mfma_f32_16x16x32_bf16 v[58:61], v[142:145], v[194:197], v[58:61]
	v_mfma_f32_16x16x32_bf16 v[46:49], v[134:137], v[210:213], v[46:49]
	v_mfma_f32_16x16x32_bf16 v[42:45], v[142:145], v[210:213], v[42:45]
	v_mfma_f32_16x16x32_bf16 v[30:33], v[134:137], v[218:221], v[30:33]
	v_mfma_f32_16x16x32_bf16 v[26:29], v[142:145], v[218:221], v[26:29]
	v_mfma_f32_16x16x32_bf16 v[14:17], v[134:137], v[226:229], v[14:17]
	v_mfma_f32_16x16x32_bf16 v[10:13], v[142:145], v[226:229], v[10:13]
	v_mfma_f32_16x16x32_bf16 v[54:57], v[146:149], v[190:193], v[54:57]
	v_mfma_f32_16x16x32_bf16 v[50:53], v[182:185], v[190:193], v[50:53]
	v_mfma_f32_16x16x32_bf16 v[38:41], v[146:149], v[206:209], v[38:41]
	v_mfma_f32_16x16x32_bf16 v[34:37], v[182:185], v[206:209], v[34:37]
	v_mfma_f32_16x16x32_bf16 v[22:25], v[146:149], v[214:217], v[22:25]
	v_mfma_f32_16x16x32_bf16 v[18:21], v[182:185], v[214:217], v[18:21]
	v_mfma_f32_16x16x32_bf16 v[6:9], v[146:149], v[222:225], v[6:9]
	v_mfma_f32_16x16x32_bf16 v[2:5], v[182:185], v[222:225], v[2:5]
	v_mfma_f32_16x16x32_bf16 v[54:57], v[150:153], v[194:197], v[54:57]
	v_mfma_f32_16x16x32_bf16 v[50:53], v[186:189], v[194:197], v[50:53]
	v_mfma_f32_16x16x32_bf16 v[38:41], v[150:153], v[210:213], v[38:41]
	v_mfma_f32_16x16x32_bf16 v[34:37], v[186:189], v[210:213], v[34:37]
	v_mfma_f32_16x16x32_bf16 v[22:25], v[150:153], v[218:221], v[22:25]
	v_mfma_f32_16x16x32_bf16 v[18:21], v[186:189], v[218:221], v[18:21]
	v_mfma_f32_16x16x32_bf16 v[6:9], v[150:153], v[226:229], v[6:9]
	v_mfma_f32_16x16x32_bf16 v[2:5], v[186:189], v[226:229], v[2:5]
	s_barrier
	s_setprio 0
	s_add_u32 s46, s46, 0x100
	s_addc_u32 s47, s47, 0
	s_add_u32 s13, s13, 0x100
	s_addc_u32 s24, s24, 0
	s_cmp_ge_u32 s78, s65
	s_mov_b32 s72, s78
	s_cbranch_scc1 .LBB0_399

; #define PG8_STAGE(bufoff, gbase, voff) do { _Pragma("unroll") for (int _i = 0; _i < 2; ++_i) \
;         __builtin_amdgcn_global_load_lds((const unsigned*)((const char*)(gbase) + (voff)[_i]), (PG8_LAS unsigned*)(lds + (bufoff) + ldsw + _i * 8192), 16, 0, 0); } while (0)
; #define PG8_LDA(dst, b, h) do { _Pragma("unroll") for (int m = 0; m < 4; ++m) _Pragma("unroll") for (int k = 0; k < 2; ++k) dst[m][k] = *(const PG8_LAS bf16x8*)(lds + PG8_SA(b, h) + aoff + m * 2048 + k * 1024); } while (0)
; #define PG8_WAIT_V(n) asm volatile("s_waitcnt vmcnt(" #n ")" ::: "memory")
; #define PG8_WAIT_L(n) asm volatile("s_waitcnt lgkmcnt(" #n ")" ::: "memory")
; #define PG8_BAR __builtin_amdgcn_s_barrier()
; template <class Epi, class Sched, bool ALIGN_EPI = false, bool SP2 = false, bool F16 = false>
; __device__ __forceinline__ void gemm_phase(PG8_LAS unsigned char* lds, const Gemm g, const Sched& S, const Epi& E) {
;     ...
;         for (int t = 0; t < nt; t += 2) {
;             const bool last = (t == nt - 2);
;             const char* a1 = cA + (size_t)(t + 1) * kstep;
;             const char* a2 = last ? nA : cA + (size_t)(t + 2) * kstep; const char* b2 = last ? nB : cB + (size_t)(t + 2) * kstep;
;             const char* a3 = a2 + kstep; const char* b3 = b2 + kstep;
;             if (last && has_next) S.a_ready(nxt);
;             if constexpr (SP2) {
;             PG8_LDB(B0, 0, 0); PG8_LDB(B1, 0, 1); PG8_SCHED; PG8_LDA(At, 0, 0); PG8_STAGE(PG8_SA(1, 1), a1 + hstepA, voffA);
;             PG8_WAIT_V(8); PG8_WAIT_L(0); PG8_BAR; PG8_MMA(0, 0, At, B0); PG8_MMA(0, 1, At, B1); PG8_BAR; PG8_SCHED;
;             PG8_LDA(At, 0, 1); PG8_STAGE(PG8_SB(0, 0), b2, voffB); PG8_STAGE(PG8_SB(0, 1), b2 + hstepB, voffB); PG8_STAGE(PG8_SA(0, 0), a2, voffA);
;             PG8_WAIT_V(8); PG8_WAIT_L(0); PG8_BAR; PG8_MMA(1, 0, At, B0); PG8_MMA(1, 1, At, B1); PG8_BAR; PG8_SCHED;
;             PG8_LDB(B0, 1, 0); PG8_LDB(B1, 1, 1); PG8_SCHED; PG8_LDA(At, 1, 0); PG8_STAGE(PG8_SA(0, 1), a2 + hstepA, voffA);
;             PG8_WAIT_V(8); PG8_WAIT_L(0); PG8_BAR; PG8_MMA(0, 0, At, B0); PG8_MMA(0, 1, At, B1); PG8_BAR; PG8_SCHED;
;             PG8_LDA(At, 1, 1); PG8_STAGE(PG8_SB(1, 0), b3, voffB); PG8_STAGE(PG8_SB(1, 1), b3 + hstepB, voffB); PG8_STAGE(PG8_SA(1, 0), a3, voffA);
;             PG8_WAIT_V(8); PG8_WAIT_L(0); PG8_BAR; PG8_MMA(1, 0, At, B0); PG8_MMA(1, 1, At, B1); PG8_BAR; PG8_SCHED;
.LBB0_562:
	s_andn2_b64 vcc, exec, s[4:5]
	s_waitcnt vmcnt(0)
	s_cbranch_vccnz .Lzk_bh
	s_add_u32 s44, s72, 0x80
	s_addc_u32 s45, s73, 0
	s_add_u32 s24, s52, 0x100
	s_addc_u32 s72, s53, 0
	s_mov_b32 s52, 0
.Lpk_bh:
	s_add_i32 s73, s52, 2
	s_add_u32 s82, s44, 0x80
	s_addc_u32 s53, s45, 0
	s_add_i32 s94, 0, 0x10000
	s_cmp_eq_u32 s74, s52
	s_cselect_b32 s53, s79, s53
	s_cselect_b32 s52, s78, s82
	s_cselect_b32 s83, s55, s72
	s_cselect_b32 s82, s54, s24
	s_add_i32 s95, 0, 0x14000
	v_add_u32_e32 v142, s94, v163
	v_add_u32_e32 v172, s95, v163
	ds_read_b128 v[130:133], v142
	ds_read_b128 v[134:137], v142 offset:1024
	ds_read_b128 v[138:141], v142 offset:2048
	ds_read_b128 v[142:145], v142 offset:3072
	ds_read_b128 v[146:149], v172
	ds_read_b128 v[150:153], v172 offset:1024
	ds_read_b128 v[182:185], v172 offset:2048
	ds_read_b128 v[186:189], v172 offset:3072
	v_lshl_add_u64 v[172:173], s[44:45], 0, v[168:169]
	s_add_i32 m0, s35, 0xc000
	ds_read_b128 v[190:193], v204
	ds_read_b128 v[194:197], v204 offset:1024
	ds_read_b128 v[206:209], v204 offset:2048
	ds_read_b128 v[210:213], v204 offset:3072
	ds_read_b128 v[214:217], v204 offset:4096
	ds_read_b128 v[218:221], v204 offset:5120
	ds_read_b128 v[222:225], v204 offset:6144
	ds_read_b128 v[226:229], v204 offset:7168
	global_load_lds_dwordx4 v[172:173], off
	v_lshl_add_u64 v[172:173], s[44:45], 0, v[170:171]
	s_add_i32 m0, s35, 0xe000
	s_nop 0
	global_load_lds_dwordx4 v[172:173], off
	s_waitcnt vmcnt(8)
	s_waitcnt lgkmcnt(0)
	s_setprio 1
	s_barrier
	v_mfma_f32_16x16x32_f16 v[122:125], v[130:133], v[190:193], 0
	v_mfma_f32_16x16x32_f16 v[126:129], v[138:141], v[190:193], 0
	v_mfma_f32_16x16x32_f16 v[110:113], v[130:133], v[206:209], 0
	v_mfma_f32_16x16x32_f16 v[106:109], v[138:141], v[206:209], 0
	v_mfma_f32_16x16x32_f16 v[94:97], v[130:133], v[214:217], 0
	v_mfma_f32_16x16x32_f16 v[90:93], v[138:141], v[214:217], 0
	v_mfma_f32_16x16x32_f16 v[78:81], v[130:133], v[222:225], 0
	v_mfma_f32_16x16x32_f16 v[74:77], v[138:141], v[222:225], 0
	v_mfma_f32_16x16x32_f16 v[122:125], v[134:137], v[194:197], v[122:125]
	v_mfma_f32_16x16x32_f16 v[126:129], v[142:145], v[194:197], v[126:129]
	v_mfma_f32_16x16x32_f16 v[110:113], v[134:137], v[210:213], v[110:113]
	v_mfma_f32_16x16x32_f16 v[106:109], v[142:145], v[210:213], v[106:109]
	v_mfma_f32_16x16x32_f16 v[94:97], v[134:137], v[218:221], v[94:97]
	v_mfma_f32_16x16x32_f16 v[90:93], v[142:145], v[218:221], v[90:93]
	v_mfma_f32_16x16x32_f16 v[78:81], v[134:137], v[226:229], v[78:81]
	v_mfma_f32_16x16x32_f16 v[74:77], v[142:145], v[226:229], v[74:77]
	v_mfma_f32_16x16x32_f16 v[118:121], v[146:149], v[190:193], 0
	v_mfma_f32_16x16x32_f16 v[114:117], v[182:185], v[190:193], 0
	v_mfma_f32_16x16x32_f16 v[102:105], v[146:149], v[206:209], 0
	v_mfma_f32_16x16x32_f16 v[98:101], v[182:185], v[206:209], 0
	v_mfma_f32_16x16x32_f16 v[86:89], v[146:149], v[214:217], 0
	v_mfma_f32_16x16x32_f16 v[82:85], v[182:185], v[214:217], 0
	v_mfma_f32_16x16x32_f16 v[70:73], v[146:149], v[222:225], 0
	v_mfma_f32_16x16x32_f16 v[66:69], v[182:185], v[222:225], 0
	v_mfma_f32_16x16x32_f16 v[118:121], v[150:153], v[194:197], v[118:121]
	v_mfma_f32_16x16x32_f16 v[114:117], v[186:189], v[194:197], v[114:117]
	v_mfma_f32_16x16x32_f16 v[102:105], v[150:153], v[210:213], v[102:105]
	v_mfma_f32_16x16x32_f16 v[98:101], v[186:189], v[210:213], v[98:101]
	v_mfma_f32_16x16x32_f16 v[86:89], v[150:153], v[218:221], v[86:89]
	v_mfma_f32_16x16x32_f16 v[82:85], v[186:189], v[218:221], v[82:85]
	v_mfma_f32_16x16x32_f16 v[70:73], v[150:153], v[226:229], v[70:73]
	v_mfma_f32_16x16x32_f16 v[66:69], v[186:189], v[226:229], v[66:69]
	s_barrier
	s_setprio 0
	s_add_i32 s94, s94, s75
	v_lshl_add_u64 v[172:173], s[82:83], 0, v[156:157]
	s_mov_b32 m0, s94
	ds_read_b128 v[190:193], v204 offset:16384
	ds_read_b128 v[194:197], v204 offset:17408
	ds_read_b128 v[206:209], v204 offset:18432
	ds_read_b128 v[210:213], v204 offset:19456
	ds_read_b128 v[214:217], v204 offset:20480
	ds_read_b128 v[218:221], v204 offset:21504
	ds_read_b128 v[222:225], v204 offset:22528
	ds_read_b128 v[226:229], v204 offset:23552
	global_load_lds_dwordx4 v[172:173], off
	s_add_i32 m0, s94, 0x2000
	v_lshl_add_u64 v[176:177], s[82:83], 0, v[160:161]
	s_add_u32 s82, s82, s48
	s_addc_u32 s83, s83, 0
	s_add_i32 s94, s95, s75
	global_load_lds_dwordx4 v[176:177], off
	v_lshl_add_u64 v[230:231], s[82:83], 0, v[156:157]
	s_mov_b32 m0, s94
	v_lshl_add_u64 v[232:233], s[82:83], 0, v[160:161]
	global_load_lds_dwordx4 v[230:231], off
	s_add_i32 m0, s94, 0x2000
	v_lshl_add_u64 v[234:235], s[52:53], 0, v[154:155]
	global_load_lds_dwordx4 v[232:233], off
	s_mov_b32 m0, s35
	v_lshl_add_u64 v[236:237], s[52:53], 0, v[158:159]
	global_load_lds_dwordx4 v[234:235], off
	s_mov_b32 m0, s2
	s_nop 0
	global_load_lds_dwordx4 v[236:237], off
	s_waitcnt vmcnt(8)
	s_waitcnt lgkmcnt(0)
	s_setprio 1
	s_barrier
; #define PG8_STAGE(bufoff, gbase, voff) do { _Pragma("unroll") for (int _i = 0; _i < 2; ++_i) \
;         __builtin_amdgcn_global_load_lds((const unsigned*)((const char*)(gbase) + (voff)[_i]), (PG8_LAS unsigned*)(lds + (bufoff) + ldsw + _i * 8192), 16, 0, 0); } while (0)
; #define PG8_LDA(dst, b, h) do { _Pragma("unroll") for (int m = 0; m < 4; ++m) _Pragma("unroll") for (int k = 0; k < 2; ++k) dst[m][k] = *(const PG8_LAS bf16x8*)(lds + PG8_SA(b, h) + aoff + m * 2048 + k * 1024); } while (0)
; #define PG8_WAIT_V(n) asm volatile("s_waitcnt vmcnt(" #n ")" ::: "memory")
; #define PG8_WAIT_L(n) asm volatile("s_waitcnt lgkmcnt(" #n ")" ::: "memory")
; #define PG8_BAR __builtin_amdgcn_s_barrier()
; template <class Epi, class Sched, bool ALIGN_EPI = false, bool SP2 = false, bool F16 = false>
; __device__ __forceinline__ void gemm_phase(PG8_LAS unsigned char* lds, const Gemm g, const Sched& S, const Epi& E) {
;     ...
;         for (int t = 0; t < nt; t += 2) {
;             const bool last = (t == nt - 2);
;             const char* a1 = cA + (size_t)(t + 1) * kstep;
;             const char* a2 = last ? nA : cA + (size_t)(t + 2) * kstep; const char* b2 = last ? nB : cB + (size_t)(t + 2) * kstep;
;             const char* a3 = a2 + kstep; const char* b3 = b2 + kstep;
;             if (last && has_next) S.a_ready(nxt);
;             if constexpr (SP2) {
;             PG8_LDB(B0, 0, 0); PG8_LDB(B1, 0, 1); PG8_SCHED; PG8_LDA(At, 0, 0); PG8_STAGE(PG8_SA(1, 1), a1 + hstepA, voffA);
;             PG8_WAIT_V(8); PG8_WAIT_L(0); PG8_BAR; PG8_MMA(0, 0, At, B0); PG8_MMA(0, 1, At, B1); PG8_BAR; PG8_SCHED;
;             PG8_LDA(At, 0, 1); PG8_STAGE(PG8_SB(0, 0), b2, voffB); PG8_STAGE(PG8_SB(0, 1), b2 + hstepB, voffB); PG8_STAGE(PG8_SA(0, 0), a2, voffA);
;             PG8_WAIT_V(8); PG8_WAIT_L(0); PG8_BAR; PG8_MMA(1, 0, At, B0); PG8_MMA(1, 1, At, B1); PG8_BAR; PG8_SCHED;
;             PG8_LDB(B0, 1, 0); PG8_LDB(B1, 1, 1); PG8_SCHED; PG8_LDA(At, 1, 0); PG8_STAGE(PG8_SA(0, 1), a2 + hstepA, voffA);
;             PG8_WAIT_V(8); PG8_WAIT_L(0); PG8_BAR; PG8_MMA(0, 0, At, B0); PG8_MMA(0, 1, At, B1); PG8_BAR; PG8_SCHED;
;             PG8_LDA(At, 1, 1); PG8_STAGE(PG8_SB(1, 0), b3, voffB); PG8_STAGE(PG8_SB(1, 1), b3 + hstepB, voffB); PG8_STAGE(PG8_SA(1, 0), a3, voffA);
;             PG8_WAIT_V(8); PG8_WAIT_L(0); PG8_BAR; PG8_MMA(1, 0, At, B0); PG8_MMA(1, 1, At, B1); PG8_BAR; PG8_SCHED;
	v_mfma_f32_16x16x32_f16 v[62:65], v[130:133], v[190:193], 0
	v_mfma_f32_16x16x32_f16 v[58:61], v[138:141], v[190:193], 0
	v_mfma_f32_16x16x32_f16 v[46:49], v[130:133], v[206:209], 0
	v_mfma_f32_16x16x32_f16 v[42:45], v[138:141], v[206:209], 0
	v_mfma_f32_16x16x32_f16 v[30:33], v[130:133], v[214:217], 0
	v_mfma_f32_16x16x32_f16 v[26:29], v[138:141], v[214:217], 0
	v_mfma_f32_16x16x32_f16 v[14:17], v[130:133], v[222:225], 0
	v_mfma_f32_16x16x32_f16 v[10:13], v[138:141], v[222:225], 0
	v_mfma_f32_16x16x32_f16 v[62:65], v[134:137], v[194:197], v[62:65]
	v_mfma_f32_16x16x32_f16 v[58:61], v[142:145], v[194:197], v[58:61]
	v_mfma_f32_16x16x32_f16 v[46:49], v[134:137], v[210:213], v[46:49]
	v_mfma_f32_16x16x32_f16 v[42:45], v[142:145], v[210:213], v[42:45]
	v_mfma_f32_16x16x32_f16 v[30:33], v[134:137], v[218:221], v[30:33]
	v_mfma_f32_16x16x32_f16 v[26:29], v[142:145], v[218:221], v[26:29]
	v_mfma_f32_16x16x32_f16 v[14:17], v[134:137], v[226:229], v[14:17]
	v_mfma_f32_16x16x32_f16 v[10:13], v[142:145], v[226:229], v[10:13]
	v_mfma_f32_16x16x32_f16 v[54:57], v[146:149], v[190:193], 0
	v_mfma_f32_16x16x32_f16 v[50:53], v[182:185], v[190:193], 0
	v_mfma_f32_16x16x32_f16 v[38:41], v[146:149], v[206:209], 0
	v_mfma_f32_16x16x32_f16 v[34:37], v[182:185], v[206:209], 0
	v_mfma_f32_16x16x32_f16 v[22:25], v[146:149], v[214:217], 0
	v_mfma_f32_16x16x32_f16 v[18:21], v[182:185], v[214:217], 0
	v_mfma_f32_16x16x32_f16 v[6:9], v[146:149], v[222:225], 0
	v_mfma_f32_16x16x32_f16 v[2:5], v[182:185], v[222:225], 0
	v_mfma_f32_16x16x32_f16 v[54:57], v[150:153], v[194:197], v[54:57]
	v_mfma_f32_16x16x32_f16 v[50:53], v[186:189], v[194:197], v[50:53]
	v_mfma_f32_16x16x32_f16 v[38:41], v[150:153], v[210:213], v[38:41]
	v_mfma_f32_16x16x32_f16 v[34:37], v[186:189], v[210:213], v[34:37]
	v_mfma_f32_16x16x32_f16 v[22:25], v[150:153], v[218:221], v[22:25]
	v_mfma_f32_16x16x32_f16 v[18:21], v[186:189], v[218:221], v[18:21]
	v_mfma_f32_16x16x32_f16 v[6:9], v[150:153], v[226:229], v[6:9]
	v_mfma_f32_16x16x32_f16 v[2:5], v[186:189], v[226:229], v[2:5]
	s_barrier
	s_setprio 0
	s_add_i32 s82, 0, 0x18000
	s_add_i32 s83, 0, 0x1c000
	v_add_u32_e32 v142, s82, v163
	v_add_u32_e32 v174, s83, v163
	ds_read_b128 v[130:133], v142
	ds_read_b128 v[134:137], v142 offset:1024
	ds_read_b128 v[138:141], v142 offset:2048
	ds_read_b128 v[142:145], v142 offset:3072
	ds_read_b128 v[146:149], v174
	ds_read_b128 v[150:153], v174 offset:1024
	ds_read_b128 v[182:185], v174 offset:2048
	ds_read_b128 v[186:189], v174 offset:3072
	s_add_u32 s52, s52, s8
	s_addc_u32 s53, s53, 0
	s_mov_b32 m0, s22
	v_lshl_add_u64 v[238:239], s[52:53], 0, v[154:155]
	ds_read_b128 v[190:193], v204 offset:32768
	ds_read_b128 v[194:197], v204 offset:33792
	ds_read_b128 v[206:209], v204 offset:34816
	ds_read_b128 v[210:213], v204 offset:35840
	ds_read_b128 v[214:217], v204 offset:36864
	ds_read_b128 v[218:221], v204 offset:37888
	ds_read_b128 v[222:225], v204 offset:38912
	ds_read_b128 v[226:229], v204 offset:39936
	global_load_lds_dwordx4 v[238:239], off
	v_lshl_add_u64 v[238:239], s[52:53], 0, v[158:159]
	s_mov_b32 m0, s23
	s_nop 0
	global_load_lds_dwordx4 v[238:239], off
	s_waitcnt vmcnt(8)
	s_waitcnt lgkmcnt(0)
	s_setprio 1
	s_barrier
	v_mfma_f32_16x16x32_f16 v[122:125], v[130:133], v[190:193], v[122:125]
	v_mfma_f32_16x16x32_f16 v[126:129], v[138:141], v[190:193], v[126:129]
	v_mfma_f32_16x16x32_f16 v[110:113], v[130:133], v[206:209], v[110:113]
	v_mfma_f32_16x16x32_f16 v[106:109], v[138:141], v[206:209], v[106:109]
	v_mfma_f32_16x16x32_f16 v[94:97], v[130:133], v[214:217], v[94:97]
	v_mfma_f32_16x16x32_f16 v[90:93], v[138:141], v[214:217], v[90:93]
	v_mfma_f32_16x16x32_f16 v[78:81], v[130:133], v[222:225], v[78:81]
	v_mfma_f32_16x16x32_f16 v[74:77], v[138:141], v[222:225], v[74:77]
	v_mfma_f32_16x16x32_f16 v[122:125], v[134:137], v[194:197], v[122:125]
	v_mfma_f32_16x16x32_f16 v[126:129], v[142:145], v[194:197], v[126:129]
	v_mfma_f32_16x16x32_f16 v[110:113], v[134:137], v[210:213], v[110:113]
	v_mfma_f32_16x16x32_f16 v[106:109], v[142:145], v[210:213], v[106:109]
	v_mfma_f32_16x16x32_f16 v[94:97], v[134:137], v[218:221], v[94:97]
	v_mfma_f32_16x16x32_f16 v[90:93], v[142:145], v[218:221], v[90:93]
	v_mfma_f32_16x16x32_f16 v[78:81], v[134:137], v[226:229], v[78:81]
	v_mfma_f32_16x16x32_f16 v[74:77], v[142:145], v[226:229], v[74:77]
	v_mfma_f32_16x16x32_f16 v[118:121], v[146:149], v[190:193], v[118:121]
	v_mfma_f32_16x16x32_f16 v[114:117], v[182:185], v[190:193], v[114:117]
	v_mfma_f32_16x16x32_f16 v[102:105], v[146:149], v[206:209], v[102:105]
	v_mfma_f32_16x16x32_f16 v[98:101], v[182:185], v[206:209], v[98:101]
	v_mfma_f32_16x16x32_f16 v[86:89], v[146:149], v[214:217], v[86:89]
	v_mfma_f32_16x16x32_f16 v[82:85], v[182:185], v[214:217], v[82:85]
	v_mfma_f32_16x16x32_f16 v[70:73], v[146:149], v[222:225], v[70:73]
	v_mfma_f32_16x16x32_f16 v[66:69], v[182:185], v[222:225], v[66:69]
	v_mfma_f32_16x16x32_f16 v[118:121], v[150:153], v[194:197], v[118:121]
	v_mfma_f32_16x16x32_f16 v[114:117], v[186:189], v[194:197], v[114:117]
	v_mfma_f32_16x16x32_f16 v[102:105], v[150:153], v[210:213], v[102:105]
	v_mfma_f32_16x16x32_f16 v[98:101], v[186:189], v[210:213], v[98:101]
	v_mfma_f32_16x16x32_f16 v[86:89], v[150:153], v[218:221], v[86:89]
	v_mfma_f32_16x16x32_f16 v[82:85], v[186:189], v[218:221], v[82:85]
	v_mfma_f32_16x16x32_f16 v[70:73], v[150:153], v[226:229], v[70:73]
	v_mfma_f32_16x16x32_f16 v[66:69], v[186:189], v[226:229], v[66:69]
	s_barrier
; #define PG8_STAGE(bufoff, gbase, voff) do { _Pragma("unroll") for (int _i = 0; _i < 2; ++_i) \
;         __builtin_amdgcn_global_load_lds((const unsigned*)((const char*)(gbase) + (voff)[_i]), (PG8_LAS unsigned*)(lds + (bufoff) + ldsw + _i * 8192), 16, 0, 0); } while (0)
; #define PG8_LDA(dst, b, h) do { _Pragma("unroll") for (int m = 0; m < 4; ++m) _Pragma("unroll") for (int k = 0; k < 2; ++k) dst[m][k] = *(const PG8_LAS bf16x8*)(lds + PG8_SA(b, h) + aoff + m * 2048 + k * 1024); } while (0)
; #define PG8_WAIT_V(n) asm volatile("s_waitcnt vmcnt(" #n ")" ::: "memory")
; #define PG8_WAIT_L(n) asm volatile("s_waitcnt lgkmcnt(" #n ")" ::: "memory")
; #define PG8_BAR __builtin_amdgcn_s_barrier()
; template <class Epi, class Sched, bool ALIGN_EPI = false, bool SP2 = false, bool F16 = false>
; __device__ __forceinline__ void gemm_phase(PG8_LAS unsigned char* lds, const Gemm g, const Sched& S, const Epi& E) {
;     ...
;         for (int t = 0; t < nt; t += 2) {
;             const bool last = (t == nt - 2);
;             const char* a1 = cA + (size_t)(t + 1) * kstep;
;             const char* a2 = last ? nA : cA + (size_t)(t + 2) * kstep; const char* b2 = last ? nB : cB + (size_t)(t + 2) * kstep;
;             const char* a3 = a2 + kstep; const char* b3 = b2 + kstep;
;             if (last && has_next) S.a_ready(nxt);
;             if constexpr (SP2) {
;             PG8_LDB(B0, 0, 0); PG8_LDB(B1, 0, 1); PG8_SCHED; PG8_LDA(At, 0, 0); PG8_STAGE(PG8_SA(1, 1), a1 + hstepA, voffA);
;             PG8_WAIT_V(8); PG8_WAIT_L(0); PG8_BAR; PG8_MMA(0, 0, At, B0); PG8_MMA(0, 1, At, B1); PG8_BAR; PG8_SCHED;
;             PG8_LDA(At, 0, 1); PG8_STAGE(PG8_SB(0, 0), b2, voffB); PG8_STAGE(PG8_SB(0, 1), b2 + hstepB, voffB); PG8_STAGE(PG8_SA(0, 0), a2, voffA);
;             PG8_WAIT_V(8); PG8_WAIT_L(0); PG8_BAR; PG8_MMA(1, 0, At, B0); PG8_MMA(1, 1, At, B1); PG8_BAR; PG8_SCHED;
;             PG8_LDB(B0, 1, 0); PG8_LDB(B1, 1, 1); PG8_SCHED; PG8_LDA(At, 1, 0); PG8_STAGE(PG8_SA(0, 1), a2 + hstepA, voffA);
;             PG8_WAIT_V(8); PG8_WAIT_L(0); PG8_BAR; PG8_MMA(0, 0, At, B0); PG8_MMA(0, 1, At, B1); PG8_BAR; PG8_SCHED;
;             PG8_LDA(At, 1, 1); PG8_STAGE(PG8_SB(1, 0), b3, voffB); PG8_STAGE(PG8_SB(1, 1), b3 + hstepB, voffB); PG8_STAGE(PG8_SA(1, 0), a3, voffA);
;             PG8_WAIT_V(8); PG8_WAIT_L(0); PG8_BAR; PG8_MMA(1, 0, At, B0); PG8_MMA(1, 1, At, B1); PG8_BAR; PG8_SCHED;
	s_setprio 0
	s_add_i32 s52, s82, s75
	v_lshl_add_u64 v[172:173], v[172:173], 0, s[92:93]
	s_mov_b32 m0, s52
	ds_read_b128 v[190:193], v204 offset:49152
	ds_read_b128 v[194:197], v204 offset:50176
	ds_read_b128 v[206:209], v204 offset:51200
	ds_read_b128 v[210:213], v204 offset:52224
	ds_read_b128 v[214:217], v204 offset:53248
	ds_read_b128 v[218:221], v204 offset:54272
	ds_read_b128 v[222:225], v204 offset:55296
	ds_read_b128 v[226:229], v204 offset:56320
	global_load_lds_dwordx4 v[172:173], off
	v_lshl_add_u64 v[172:173], v[176:177], 0, s[92:93]
	s_add_i32 m0, s52, 0x2000
	s_add_i32 s52, s83, s75
	global_load_lds_dwordx4 v[172:173], off
	v_lshl_add_u64 v[172:173], v[230:231], 0, s[92:93]
	s_mov_b32 m0, s52
	s_nop 0
	global_load_lds_dwordx4 v[172:173], off
	v_lshl_add_u64 v[172:173], v[232:233], 0, s[92:93]
	s_add_i32 m0, s52, 0x2000
	s_nop 0
	global_load_lds_dwordx4 v[172:173], off
	v_lshl_add_u64 v[172:173], v[234:235], 0, s[92:93]
	s_mov_b32 m0, s61
	s_nop 0
	global_load_lds_dwordx4 v[172:173], off
	v_lshl_add_u64 v[172:173], v[236:237], 0, s[92:93]
	s_mov_b32 m0, s18
	s_nop 0
	global_load_lds_dwordx4 v[172:173], off
	s_waitcnt vmcnt(8)
	s_waitcnt lgkmcnt(0)
	s_setprio 1
	s_barrier
	v_mfma_f32_16x16x32_f16 v[62:65], v[130:133], v[190:193], v[62:65]
	v_mfma_f32_16x16x32_f16 v[58:61], v[138:141], v[190:193], v[58:61]
	v_mfma_f32_16x16x32_f16 v[46:49], v[130:133], v[206:209], v[46:49]
	v_mfma_f32_16x16x32_f16 v[42:45], v[138:141], v[206:209], v[42:45]
	v_mfma_f32_16x16x32_f16 v[30:33], v[130:133], v[214:217], v[30:33]
	v_mfma_f32_16x16x32_f16 v[26:29], v[138:141], v[214:217], v[26:29]
	v_mfma_f32_16x16x32_f16 v[14:17], v[130:133], v[222:225], v[14:17]
	v_mfma_f32_16x16x32_f16 v[10:13], v[138:141], v[222:225], v[10:13]
	v_mfma_f32_16x16x32_f16 v[62:65], v[134:137], v[194:197], v[62:65]
	v_mfma_f32_16x16x32_f16 v[58:61], v[142:145], v[194:197], v[58:61]
	v_mfma_f32_16x16x32_f16 v[46:49], v[134:137], v[210:213], v[46:49]
	v_mfma_f32_16x16x32_f16 v[42:45], v[142:145], v[210:213], v[42:45]
	v_mfma_f32_16x16x32_f16 v[30:33], v[134:137], v[218:221], v[30:33]
	v_mfma_f32_16x16x32_f16 v[26:29], v[142:145], v[218:221], v[26:29]
	v_mfma_f32_16x16x32_f16 v[14:17], v[134:137], v[226:229], v[14:17]
	v_mfma_f32_16x16x32_f16 v[10:13], v[142:145], v[226:229], v[10:13]
	v_mfma_f32_16x16x32_f16 v[54:57], v[146:149], v[190:193], v[54:57]
	v_mfma_f32_16x16x32_f16 v[50:53], v[182:185], v[190:193], v[50:53]
	v_mfma_f32_16x16x32_f16 v[38:41], v[146:149], v[206:209], v[38:41]
	v_mfma_f32_16x16x32_f16 v[34:37], v[182:185], v[206:209], v[34:37]
	v_mfma_f32_16x16x32_f16 v[22:25], v[146:149], v[214:217], v[22:25]
	v_mfma_f32_16x16x32_f16 v[18:21], v[182:185], v[214:217], v[18:21]
	v_mfma_f32_16x16x32_f16 v[6:9], v[146:149], v[222:225], v[6:9]
	v_mfma_f32_16x16x32_f16 v[2:5], v[182:185], v[222:225], v[2:5]
	v_mfma_f32_16x16x32_f16 v[54:57], v[150:153], v[194:197], v[54:57]
	v_mfma_f32_16x16x32_f16 v[50:53], v[186:189], v[194:197], v[50:53]
	v_mfma_f32_16x16x32_f16 v[38:41], v[150:153], v[210:213], v[38:41]
	v_mfma_f32_16x16x32_f16 v[34:37], v[186:189], v[210:213], v[34:37]
	v_mfma_f32_16x16x32_f16 v[22:25], v[150:153], v[218:221], v[22:25]
	v_mfma_f32_16x16x32_f16 v[18:21], v[186:189], v[218:221], v[18:21]
	v_mfma_f32_16x16x32_f16 v[6:9], v[150:153], v[226:229], v[6:9]
	v_mfma_f32_16x16x32_f16 v[2:5], v[186:189], v[226:229], v[2:5]
	s_barrier
	s_setprio 0
	s_add_u32 s44, s44, 0x100
	s_addc_u32 s45, s45, 0
	s_add_u32 s24, s24, 0x100
	s_addc_u32 s72, s72, 0
	s_cmp_ge_u32 s73, s65
	s_mov_b32 s52, s73
	s_cbranch_scc1 .LBB0_565

; template <class Epi, class Sched, bool ALIGN_EPI = false, bool SP2 = false, bool F16 = false>
; __device__ __forceinline__ void gemm_phase(PG8_LAS unsigned char* lds, const Gemm g, const Sched& S, const Epi& E) {
;     ...
;     f32x4 acc[2][2][4][2];
; #pragma unroll
;     for (int a = 0; a < 2; ++a)
; #pragma unroll
;         for (int b = 0; b < 2; ++b)
; #pragma unroll
;             for (int m = 0; m < 4; ++m)
; #pragma unroll
;                 for (int n = 0; n < 2; ++n) acc[a][b][m][n] = (f32x4){0.f, 0.f, 0.f, 0.f};
.Lzk_bh:
	v_mov_b64_e32 v[2:3], 0
	v_mov_b64_e32 v[4:5], 0
	v_mov_b64_e32 v[6:7], 0
	v_mov_b64_e32 v[8:9], 0
	v_mov_b64_e32 v[10:11], 0
	v_mov_b64_e32 v[12:13], 0
	v_mov_b64_e32 v[14:15], 0
	v_mov_b64_e32 v[16:17], 0
	v_mov_b64_e32 v[18:19], 0
	v_mov_b64_e32 v[20:21], 0
	v_mov_b64_e32 v[22:23], 0
	v_mov_b64_e32 v[24:25], 0
	v_mov_b64_e32 v[26:27], 0
	v_mov_b64_e32 v[28:29], 0
	v_mov_b64_e32 v[30:31], 0
	v_mov_b64_e32 v[32:33], 0
	v_mov_b64_e32 v[34:35], 0
	v_mov_b64_e32 v[36:37], 0
	v_mov_b64_e32 v[38:39], 0
	v_mov_b64_e32 v[40:41], 0
	v_mov_b64_e32 v[42:43], 0
	v_mov_b64_e32 v[44:45], 0
	v_mov_b64_e32 v[46:47], 0
	v_mov_b64_e32 v[48:49], 0
	v_mov_b64_e32 v[50:51], 0
	v_mov_b64_e32 v[52:53], 0
	v_mov_b64_e32 v[54:55], 0
	v_mov_b64_e32 v[56:57], 0
	v_mov_b64_e32 v[58:59], 0
	v_mov_b64_e32 v[60:61], 0
	v_mov_b64_e32 v[62:63], 0
	v_mov_b64_e32 v[64:65], 0
	v_mov_b64_e32 v[66:67], 0
	v_mov_b64_e32 v[68:69], 0
	v_mov_b64_e32 v[70:71], 0
	v_mov_b64_e32 v[72:73], 0
	v_mov_b64_e32 v[74:75], 0
	v_mov_b64_e32 v[76:77], 0
	v_mov_b64_e32 v[78:79], 0
	v_mov_b64_e32 v[80:81], 0
	v_mov_b64_e32 v[82:83], 0
	v_mov_b64_e32 v[84:85], 0
	v_mov_b64_e32 v[86:87], 0
	v_mov_b64_e32 v[88:89], 0
	v_mov_b64_e32 v[90:91], 0
	v_mov_b64_e32 v[92:93], 0
	v_mov_b64_e32 v[94:95], 0
	v_mov_b64_e32 v[96:97], 0
	v_mov_b64_e32 v[98:99], 0
	v_mov_b64_e32 v[100:101], 0
	v_mov_b64_e32 v[102:103], 0
	v_mov_b64_e32 v[104:105], 0
	v_mov_b64_e32 v[106:107], 0
	v_mov_b64_e32 v[108:109], 0
	v_mov_b64_e32 v[110:111], 0
	v_mov_b64_e32 v[112:113], 0
	v_mov_b64_e32 v[114:115], 0
	v_mov_b64_e32 v[116:117], 0
	v_mov_b64_e32 v[118:119], 0
	v_mov_b64_e32 v[120:121], 0
	v_mov_b64_e32 v[122:123], 0
	v_mov_b64_e32 v[124:125], 0
	v_mov_b64_e32 v[126:127], 0
	v_mov_b64_e32 v[128:129], 0
	s_branch .LBB0_565
